# residual-GEMM epilogues: base loads software-pipelined 8 steps ahead with counted vmcnt (plus GEMM#1 loop-top vmcnt(0) removed)
# speedup vs baseline: 1.0020x; 1.0020x over previous
; #define PG8_LAS __attribute__((address_space(3)))
; __device__ __forceinline__ unsigned cvt_pk_bf16(float lo, float hi) { const f32x2_t v = {lo, hi}; const bf16x2_t b = __builtin_convertvector(v, bf16x2_t); return __builtin_bit_cast(unsigned, b); }
;     __device__ __forceinline__ void operator()(const f32x4 (&acc)[2][2][4][2], const Unit& u, int wr, int wc, int fr, int fq, const PG8_LAS float*) const {
;         const int row0 = u.pm * BM + wr * 64 + fr; const int col0 = u.pn * BM + wc * 32 + 8 * fq;
; #pragma unroll
;         for (int ai = 0; ai < 2; ++ai)
; #pragma unroll
;             for (int m = 0; m < 4; ++m) { const int row = row0 + ai * HALF + m * 16; const size_t off = (size_t)row * ldc + col0; float ss = 0.f;
; #pragma unroll
;                 for (int bj = 0; bj < 2; ++bj) {
;                     const f32x4 b0 = *(const f32x4*)(base + off + bj * HALF), b1 = *(const f32x4*)(base + off + bj * HALF + 4);
;                     const f32x4 v0 = b0 + acc[ai][bj][m][0], v1 = b1 + acc[ai][bj][m][1];
;                     *(f32x4*)(out + off + bj * HALF) = v0; *(f32x4*)(out + off + bj * HALF + 4) = v1;
;                     if (xb) { u32x4 w; w.x = cvt_pk_bf16(v0[0], v0[1]); w.y = cvt_pk_bf16(v0[2], v0[3]); w.z = cvt_pk_bf16(v1[0], v1[1]); w.w = cvt_pk_bf16(v1[2], v1[3]);
;                         *(u32x4*)(xb + off + bj * HALF) = w;
;                         ss += ((v0[0] * v0[0] + v0[1] * v0[1]) + (v0[2] * v0[2] + v0[3] * v0[3])) + ((v1[0] * v1[0] + v1[1] * v1[1]) + (v1[2] * v1[2] + v1[3] * v1[3])); } }
;                 if (xb) { ss += __shfl_xor(ss, 16); ss += __shfl_xor(ss, 32); if (fq == 0) ssq[(size_t)row * 16 + u.pn * 4 + wc] = ss; } }
.LBB0_661:
	v_lshl_add_u32 v146, s22, 8, v148
	v_lshl_or_b32 v144, s6, 8, v150
	v_ashrrev_i32_e32 v147, 31, v146
	v_ashrrev_i32_e32 v145, 31, v144
	v_lshlrev_b64 v[156:157], 10, v[146:147]
	v_lshl_add_u64 v[164:165], v[156:157], 0, v[144:145]
	v_readlane_b32 s48, v254, 3
	v_lshlrev_b64 v[168:169], 2, v[164:165]
	v_readlane_b32 s49, v254, 4
	v_readlane_b32 s22, v254, 39
	v_readlane_b32 s23, v254, 40
	v_lshl_add_u64 v[170:171], s[48:49], 0, v[168:169]
	v_mov_b32_e32 v174, v170
	v_mov_b32_e32 v175, v171
	s_mov_b64 s[98:99], 0x10000
	s_mov_b64 s[100:101], 0x50000
	global_load_dwordx4 v[176:179], v[174:175], off
	global_load_dwordx4 v[180:183], v[174:175], off offset:16
	global_load_dwordx4 v[184:187], v[174:175], off offset:512
	global_load_dwordx4 v[188:191], v[174:175], off offset:528
	v_lshl_add_u64 v[174:175], v[174:175], 0, s[98:99]
	global_load_dwordx4 v[192:195], v[174:175], off
	global_load_dwordx4 v[196:199], v[174:175], off offset:16
	global_load_dwordx4 v[200:203], v[174:175], off offset:512
	global_load_dwordx4 v[204:207], v[174:175], off offset:528
	v_lshl_add_u64 v[174:175], v[174:175], 0, s[98:99]
	global_load_dwordx4 v[208:211], v[174:175], off
	global_load_dwordx4 v[212:215], v[174:175], off offset:16
	global_load_dwordx4 v[216:219], v[174:175], off offset:512
	global_load_dwordx4 v[228:231], v[174:175], off offset:528
	v_lshl_add_u64 v[174:175], v[174:175], 0, s[98:99]
	global_load_dwordx4 v[232:235], v[174:175], off
	global_load_dwordx4 v[236:239], v[174:175], off offset:16
	global_load_dwordx4 v[240:243], v[174:175], off offset:512
	global_load_dwordx4 v[244:247], v[174:175], off offset:528
	v_lshl_add_u64 v[174:175], v[174:175], 0, s[100:101]
	v_lshl_add_u64 v[164:165], v[164:165], 1, s[22:23]
	v_lshl_add_u64 v[172:173], s[68:69], 0, v[168:169]
	v_xor_b32_e32 v155, 32, v154
	s_lshl_b32 s22, s6, 2
	s_ashr_i32 s23, s22, 31
	v_readlane_b32 s50, v254, 5
	v_readlane_b32 s51, v254, 6
	v_readlane_b32 s52, v254, 7
	v_readlane_b32 s53, v254, 8
	v_readlane_b32 s54, v254, 9
	v_readlane_b32 s55, v254, 10
	v_readlane_b32 s56, v254, 11
	v_readlane_b32 s57, v254, 12
	v_readlane_b32 s58, v254, 13
	v_readlane_b32 s59, v254, 14
	v_readlane_b32 s60, v254, 15
	v_readlane_b32 s61, v254, 16
	v_readlane_b32 s62, v254, 17
	v_readlane_b32 s63, v254, 18
	s_waitcnt vmcnt(14)
	v_pk_add_f32 v[126:127], v[126:127], v[178:179]
	v_pk_add_f32 v[124:125], v[124:125], v[176:177]
	v_pk_add_f32 v[158:159], v[122:123], v[182:183]
	v_pk_add_f32 v[156:157], v[120:121], v[180:181]
	v_cvt_pk_bf16_f32 v120, v124, v125
	v_cvt_pk_bf16_f32 v121, v126, v127
	v_cvt_pk_bf16_f32 v122, v156, v157
	v_cvt_pk_bf16_f32 v123, v158, v159
	global_store_dwordx4 v[172:173], v[124:127], off
	global_store_dwordx4 v[172:173], v[156:159], off offset:16
	global_store_dwordx4 v[164:165], v[120:123], off
	global_load_dwordx4 v[176:179], v[174:175], off
	global_load_dwordx4 v[180:183], v[174:175], off offset:16
	s_nop 0
	v_mul_f32_e32 v122, v125, v125
	v_mul_f32_e32 v123, v127, v127
	v_mul_f32_e32 v125, v157, v157
	v_mul_f32_e32 v127, v159, v159
	v_fmac_f32_e32 v122, v124, v124
	v_fmac_f32_e32 v123, v126, v126
	v_fmac_f32_e32 v125, v156, v156
	v_fmac_f32_e32 v127, v158, v158
	v_add_f32_e32 v122, v122, v123
	v_add_f32_e32 v123, v125, v127
	v_add_f32_e32 v126, v122, v123
	v_and_b32_e32 v121, 64, v154
	v_xor_b32_e32 v120, 16, v154
	v_add_u32_e32 v121, 64, v121
	v_cmp_lt_i32_e32 vcc, v120, v121
	s_waitcnt vmcnt(18)
	v_pk_add_f32 v[118:119], v[118:119], v[186:187]
	v_pk_add_f32 v[116:117], v[116:117], v[184:185]
	s_waitcnt vmcnt(17)
	v_pk_add_f32 v[124:125], v[114:115], v[190:191]
	v_pk_add_f32 v[122:123], v[112:113], v[188:189]
	v_mul_f32_e32 v112, v117, v117
	v_mul_f32_e32 v113, v119, v119
	v_mul_f32_e32 v114, v123, v123
	v_mul_f32_e32 v115, v125, v125
	v_fmac_f32_e32 v112, v116, v116
	v_fmac_f32_e32 v113, v118, v118
	v_fmac_f32_e32 v114, v122, v122
	v_fmac_f32_e32 v115, v124, v124
	v_add_f32_e32 v112, v112, v113
	v_add_f32_e32 v113, v114, v115
	v_cndmask_b32_e32 v120, v154, v120, vcc
	v_add_f32_e32 v112, v112, v113
	v_lshlrev_b32_e32 v120, 2, v120
	v_add_f32_e32 v112, v126, v112
	ds_bpermute_b32 v113, v120, v112
	v_cmp_lt_i32_e32 vcc, v155, v121
	global_store_dwordx4 v[172:173], v[116:119], off offset:512
	global_store_dwordx4 v[172:173], v[122:125], off offset:528
	v_cndmask_b32_e32 v114, v154, v155, vcc
	v_lshlrev_b32_e32 v114, 2, v114
	s_waitcnt lgkmcnt(0)
	v_add_f32_e32 v112, v112, v113
	ds_bpermute_b32 v113, v114, v112
	v_cvt_pk_bf16_f32 v116, v116, v117
	v_cvt_pk_bf16_f32 v117, v118, v119
	v_cvt_pk_bf16_f32 v118, v122, v123
	v_cvt_pk_bf16_f32 v119, v124, v125
	global_store_dwordx4 v[164:165], v[116:119], off offset:256
	s_and_saveexec_b64 s[24:25], s[2:3]
	s_cbranch_execz .LBB0_663
	v_readlane_b32 s26, v254, 41
	s_waitcnt lgkmcnt(0)
	v_add_f32_e32 v115, v112, v113
	v_lshlrev_b64 v[112:113], 6, v[146:147]
	v_readlane_b32 s27, v254, 42
	s_lshl_b32 s6, s38, 2
	s_nop 0
	v_lshl_add_u64 v[112:113], s[26:27], 0, v[112:113]
	v_lshl_add_u64 v[112:113], s[22:23], 2, v[112:113]
	v_lshl_add_u64 v[112:113], v[112:113], 0, s[6:7]
	global_store_dword v[112:113], v115, off
; __device__ __forceinline__ unsigned cvt_pk_bf16(float lo, float hi) { const f32x2_t v = {lo, hi}; const bf16x2_t b = __builtin_convertvector(v, bf16x2_t); return __builtin_bit_cast(unsigned, b); }
;     __device__ __forceinline__ void operator()(const f32x4 (&acc)[2][2][4][2], const Unit& u, int wr, int wc, int fr, int fq, const PG8_LAS float*) const {
;     ...
;             for (int m = 0; m < 4; ++m) { const int row = row0 + ai * HALF + m * 16; const size_t off = (size_t)row * ldc + col0; float ss = 0.f;
; #pragma unroll
;                 for (int bj = 0; bj < 2; ++bj) {
;                     const f32x4 b0 = *(const f32x4*)(base + off + bj * HALF), b1 = *(const f32x4*)(base + off + bj * HALF + 4);
;                     const f32x4 v0 = b0 + acc[ai][bj][m][0], v1 = b1 + acc[ai][bj][m][1];
;                     *(f32x4*)(out + off + bj * HALF) = v0; *(f32x4*)(out + off + bj * HALF + 4) = v1;
;                     if (xb) { u32x4 w; w.x = cvt_pk_bf16(v0[0], v0[1]); w.y = cvt_pk_bf16(v0[2], v0[3]); w.z = cvt_pk_bf16(v1[0], v1[1]); w.w = cvt_pk_bf16(v1[2], v1[3]);
;                         *(u32x4*)(xb + off + bj * HALF) = w;
;                         ss += ((v0[0] * v0[0] + v0[1] * v0[1]) + (v0[2] * v0[2] + v0[3] * v0[3])) + ((v1[0] * v1[0] + v1[1] * v1[1]) + (v1[2] * v1[2] + v1[3] * v1[3])); } }
;                 if (xb) { ss += __shfl_xor(ss, 16); ss += __shfl_xor(ss, 32); if (fq == 0) ssq[(size_t)row * 16 + u.pn * 4 + wc] = ss; } }
.LBB0_663:
	s_or_b64 exec, exec, s[24:25]
	v_or_b32_e32 v112, 16, v146
	s_waitcnt lgkmcnt(0)
	v_ashrrev_i32_e32 v113, 31, v112
	v_lshlrev_b64 v[116:117], 10, v[112:113]
	v_lshl_add_u64 v[126:127], v[116:117], 0, v[144:145]
	v_readlane_b32 s48, v254, 3
	v_lshlrev_b64 v[156:157], 2, v[126:127]
	v_readlane_b32 s49, v254, 4
	v_readlane_b32 s24, v254, 39
	v_readlane_b32 s25, v254, 40
	v_lshl_add_u64 v[158:159], s[48:49], 0, v[156:157]
	global_load_dwordx4 v[184:187], v[174:175], off offset:512
	global_load_dwordx4 v[188:191], v[174:175], off offset:528
	v_lshl_add_u64 v[174:175], v[174:175], 0, s[98:99]
	v_lshl_add_u64 v[126:127], v[126:127], 1, s[24:25]
	v_lshl_add_u64 v[156:157], s[68:69], 0, v[156:157]
	v_readlane_b32 s50, v254, 5
	v_readlane_b32 s51, v254, 6
	v_readlane_b32 s52, v254, 7
	v_readlane_b32 s53, v254, 8
	v_readlane_b32 s54, v254, 9
	v_readlane_b32 s55, v254, 10
	v_readlane_b32 s56, v254, 11
	v_readlane_b32 s57, v254, 12
	v_readlane_b32 s58, v254, 13
	v_readlane_b32 s59, v254, 14
	v_readlane_b32 s60, v254, 15
	v_readlane_b32 s61, v254, 16
	v_readlane_b32 s62, v254, 17
	v_readlane_b32 s63, v254, 18
	s_waitcnt vmcnt(21)
	v_pk_add_f32 v[110:111], v[110:111], v[194:195]
	v_pk_add_f32 v[108:109], v[108:109], v[192:193]
	s_waitcnt vmcnt(20)
	v_pk_add_f32 v[106:107], v[106:107], v[198:199]
	v_pk_add_f32 v[104:105], v[104:105], v[196:197]
	v_cvt_pk_bf16_f32 v116, v108, v109
	v_cvt_pk_bf16_f32 v117, v110, v111
	v_cvt_pk_bf16_f32 v118, v104, v105
	v_cvt_pk_bf16_f32 v119, v106, v107
	global_store_dwordx4 v[156:157], v[108:111], off
	global_store_dwordx4 v[156:157], v[104:107], off offset:16
	global_store_dwordx4 v[126:127], v[116:119], off
	global_load_dwordx4 v[192:195], v[174:175], off
	global_load_dwordx4 v[196:199], v[174:175], off offset:16
	s_nop 0
	v_mul_f32_e32 v109, v109, v109
	v_mul_f32_e32 v111, v111, v111
	v_mul_f32_e32 v105, v105, v105
	v_mul_f32_e32 v107, v107, v107
	v_fmac_f32_e32 v109, v108, v108
	v_fmac_f32_e32 v111, v110, v110
	v_fmac_f32_e32 v105, v104, v104
	v_fmac_f32_e32 v107, v106, v106
	v_add_f32_e32 v104, v109, v111
	v_add_f32_e32 v105, v105, v107
	v_add_f32_e32 v108, v104, v105
	s_waitcnt vmcnt(24)
	v_pk_add_f32 v[102:103], v[102:103], v[202:203]
	v_pk_add_f32 v[100:101], v[100:101], v[200:201]
	s_waitcnt vmcnt(23)
	v_pk_add_f32 v[106:107], v[98:99], v[206:207]
	v_pk_add_f32 v[104:105], v[96:97], v[204:205]
	v_mul_f32_e32 v96, v101, v101
	v_mul_f32_e32 v97, v103, v103
	v_mul_f32_e32 v98, v105, v105
	v_mul_f32_e32 v99, v107, v107
	v_fmac_f32_e32 v96, v100, v100
	v_fmac_f32_e32 v97, v102, v102
	v_fmac_f32_e32 v98, v104, v104
	v_fmac_f32_e32 v99, v106, v106
	v_add_f32_e32 v96, v96, v97
	v_add_f32_e32 v97, v98, v99
	v_add_f32_e32 v96, v96, v97
	v_add_f32_e32 v96, v108, v96
	ds_bpermute_b32 v97, v120, v96
	global_store_dwordx4 v[156:157], v[100:103], off offset:512
	global_store_dwordx4 v[156:157], v[104:107], off offset:528
	v_cvt_pk_bf16_f32 v98, v100, v101
	v_cvt_pk_bf16_f32 v99, v102, v103
	v_cvt_pk_bf16_f32 v100, v104, v105
	s_waitcnt lgkmcnt(0)
	v_add_f32_e32 v96, v96, v97
	ds_bpermute_b32 v97, v114, v96
	v_cvt_pk_bf16_f32 v101, v106, v107
	global_store_dwordx4 v[126:127], v[98:101], off offset:256
	s_and_saveexec_b64 s[24:25], s[2:3]
	s_cbranch_execz .LBB0_665
	v_readlane_b32 s26, v254, 41
	s_waitcnt lgkmcnt(0)
	v_add_f32_e32 v98, v96, v97
	v_lshlrev_b64 v[96:97], 6, v[112:113]
	v_readlane_b32 s27, v254, 42
	s_lshl_b32 s6, s38, 2
	s_nop 0
	v_lshl_add_u64 v[96:97], s[26:27], 0, v[96:97]
	v_lshl_add_u64 v[96:97], s[22:23], 2, v[96:97]
	v_lshl_add_u64 v[96:97], v[96:97], 0, s[6:7]
	global_store_dword v[96:97], v98, off
.LBB0_665:
	s_or_b64 exec, exec, s[24:25]
	v_or_b32_e32 v96, 32, v146
	s_waitcnt lgkmcnt(0)
	v_ashrrev_i32_e32 v97, 31, v96
	v_lshlrev_b64 v[98:99], 10, v[96:97]
	v_lshl_add_u64 v[106:107], v[98:99], 0, v[144:145]
	v_readlane_b32 s48, v254, 3
	v_lshlrev_b64 v[108:109], 2, v[106:107]
	v_readlane_b32 s49, v254, 4
	v_readlane_b32 s24, v254, 39
	v_readlane_b32 s25, v254, 40
	v_lshl_add_u64 v[110:111], s[48:49], 0, v[108:109]
	global_load_dwordx4 v[200:203], v[174:175], off offset:512
	global_load_dwordx4 v[204:207], v[174:175], off offset:528
	v_lshl_add_u64 v[174:175], v[174:175], 0, s[98:99]
	v_lshl_add_u64 v[106:107], v[106:107], 1, s[24:25]
	v_lshl_add_u64 v[108:109], s[68:69], 0, v[108:109]
	v_readlane_b32 s50, v254, 5
	v_readlane_b32 s51, v254, 6
	v_readlane_b32 s52, v254, 7
	v_readlane_b32 s53, v254, 8
	v_readlane_b32 s54, v254, 9
	v_readlane_b32 s55, v254, 10
	v_readlane_b32 s56, v254, 11
	v_readlane_b32 s57, v254, 12
	v_readlane_b32 s58, v254, 13
	v_readlane_b32 s59, v254, 14
	v_readlane_b32 s60, v254, 15
	v_readlane_b32 s61, v254, 16
	v_readlane_b32 s62, v254, 17
	v_readlane_b32 s63, v254, 18
	s_waitcnt vmcnt(27)
	v_pk_add_f32 v[94:95], v[94:95], v[210:211]
	v_pk_add_f32 v[92:93], v[92:93], v[208:209]
	s_waitcnt vmcnt(26)
	v_pk_add_f32 v[90:91], v[90:91], v[214:215]
	v_pk_add_f32 v[88:89], v[88:89], v[212:213]
	v_cvt_pk_bf16_f32 v98, v92, v93
	v_cvt_pk_bf16_f32 v99, v94, v95
	v_cvt_pk_bf16_f32 v100, v88, v89
	v_cvt_pk_bf16_f32 v101, v90, v91
	global_store_dwordx4 v[108:109], v[92:95], off
	global_store_dwordx4 v[108:109], v[88:91], off offset:16
	global_store_dwordx4 v[106:107], v[98:101], off
	global_load_dwordx4 v[208:211], v[174:175], off
	global_load_dwordx4 v[212:215], v[174:175], off offset:16
	s_nop 0
	v_mul_f32_e32 v93, v93, v93
	v_mul_f32_e32 v95, v95, v95
	v_mul_f32_e32 v89, v89, v89
	v_mul_f32_e32 v91, v91, v91
	v_fmac_f32_e32 v93, v92, v92
	v_fmac_f32_e32 v95, v94, v94
	v_fmac_f32_e32 v89, v88, v88
	v_fmac_f32_e32 v91, v90, v90
	v_add_f32_e32 v88, v93, v95
	v_add_f32_e32 v89, v89, v91
	v_add_f32_e32 v92, v88, v89
	s_waitcnt vmcnt(30)
	v_pk_add_f32 v[86:87], v[86:87], v[218:219]
	v_pk_add_f32 v[84:85], v[84:85], v[216:217]
	s_waitcnt vmcnt(29)
	v_pk_add_f32 v[90:91], v[82:83], v[230:231]
	v_pk_add_f32 v[88:89], v[80:81], v[228:229]
	v_mul_f32_e32 v80, v85, v85
	v_mul_f32_e32 v81, v87, v87
	v_mul_f32_e32 v82, v89, v89
	v_mul_f32_e32 v83, v91, v91
	v_fmac_f32_e32 v80, v84, v84
	v_fmac_f32_e32 v81, v86, v86
	v_fmac_f32_e32 v82, v88, v88
	v_fmac_f32_e32 v83, v90, v90
	v_add_f32_e32 v80, v80, v81
	v_add_f32_e32 v81, v82, v83
	v_add_f32_e32 v80, v80, v81
	v_add_f32_e32 v80, v92, v80
	ds_bpermute_b32 v81, v120, v80
	global_store_dwordx4 v[108:109], v[84:87], off offset:512
	global_store_dwordx4 v[108:109], v[88:91], off offset:528
	v_cvt_pk_bf16_f32 v82, v84, v85
	v_cvt_pk_bf16_f32 v83, v86, v87
	v_cvt_pk_bf16_f32 v84, v88, v89
	s_waitcnt lgkmcnt(0)
	v_add_f32_e32 v80, v80, v81
	ds_bpermute_b32 v81, v114, v80
	v_cvt_pk_bf16_f32 v85, v90, v91
	global_store_dwordx4 v[106:107], v[82:85], off offset:256
	s_and_saveexec_b64 s[24:25], s[2:3]
	s_cbranch_execz .LBB0_667
; __device__ __forceinline__ unsigned cvt_pk_bf16(float lo, float hi) { const f32x2_t v = {lo, hi}; const bf16x2_t b = __builtin_convertvector(v, bf16x2_t); return __builtin_bit_cast(unsigned, b); }
;     __device__ __forceinline__ void operator()(const f32x4 (&acc)[2][2][4][2], const Unit& u, int wr, int wc, int fr, int fq, const PG8_LAS float*) const {
;     ...
;             for (int m = 0; m < 4; ++m) { const int row = row0 + ai * HALF + m * 16; const size_t off = (size_t)row * ldc + col0; float ss = 0.f;
; #pragma unroll
;                 for (int bj = 0; bj < 2; ++bj) {
;                     const f32x4 b0 = *(const f32x4*)(base + off + bj * HALF), b1 = *(const f32x4*)(base + off + bj * HALF + 4);
;                     const f32x4 v0 = b0 + acc[ai][bj][m][0], v1 = b1 + acc[ai][bj][m][1];
;                     *(f32x4*)(out + off + bj * HALF) = v0; *(f32x4*)(out + off + bj * HALF + 4) = v1;
;                     if (xb) { u32x4 w; w.x = cvt_pk_bf16(v0[0], v0[1]); w.y = cvt_pk_bf16(v0[2], v0[3]); w.z = cvt_pk_bf16(v1[0], v1[1]); w.w = cvt_pk_bf16(v1[2], v1[3]);
;                         *(u32x4*)(xb + off + bj * HALF) = w;
;                         ss += ((v0[0] * v0[0] + v0[1] * v0[1]) + (v0[2] * v0[2] + v0[3] * v0[3])) + ((v1[0] * v1[0] + v1[1] * v1[1]) + (v1[2] * v1[2] + v1[3] * v1[3])); } }
;                 if (xb) { ss += __shfl_xor(ss, 16); ss += __shfl_xor(ss, 32); if (fq == 0) ssq[(size_t)row * 16 + u.pn * 4 + wc] = ss; } }
	v_readlane_b32 s26, v254, 41
	s_waitcnt lgkmcnt(0)
	v_add_f32_e32 v82, v80, v81
	v_lshlrev_b64 v[80:81], 6, v[96:97]
	v_readlane_b32 s27, v254, 42
	s_lshl_b32 s6, s38, 2
	s_nop 0
	v_lshl_add_u64 v[80:81], s[26:27], 0, v[80:81]
	v_lshl_add_u64 v[80:81], s[22:23], 2, v[80:81]
	v_lshl_add_u64 v[80:81], v[80:81], 0, s[6:7]
	global_store_dword v[80:81], v82, off
.LBB0_667:
	s_or_b64 exec, exec, s[24:25]
	v_or_b32_e32 v80, 48, v146
	s_waitcnt lgkmcnt(0)
	v_ashrrev_i32_e32 v81, 31, v80
	v_lshlrev_b64 v[82:83], 10, v[80:81]
	v_lshl_add_u64 v[90:91], v[82:83], 0, v[144:145]
	v_readlane_b32 s48, v254, 3
	v_lshlrev_b64 v[92:93], 2, v[90:91]
	v_readlane_b32 s49, v254, 4
	v_readlane_b32 s24, v254, 39
	v_readlane_b32 s25, v254, 40
	v_lshl_add_u64 v[94:95], s[48:49], 0, v[92:93]
	global_load_dwordx4 v[216:219], v[174:175], off offset:512
	global_load_dwordx4 v[228:231], v[174:175], off offset:528
	v_lshl_add_u64 v[174:175], v[174:175], 0, s[98:99]
	v_lshl_add_u64 v[90:91], v[90:91], 1, s[24:25]
	v_lshl_add_u64 v[92:93], s[68:69], 0, v[92:93]
	v_readlane_b32 s50, v254, 5
	v_readlane_b32 s51, v254, 6
	v_readlane_b32 s52, v254, 7
	v_readlane_b32 s53, v254, 8
	v_readlane_b32 s54, v254, 9
	v_readlane_b32 s55, v254, 10
	v_readlane_b32 s56, v254, 11
	v_readlane_b32 s57, v254, 12
	v_readlane_b32 s58, v254, 13
	v_readlane_b32 s59, v254, 14
	v_readlane_b32 s60, v254, 15
	v_readlane_b32 s61, v254, 16
	v_readlane_b32 s62, v254, 17
	v_readlane_b32 s63, v254, 18
	s_waitcnt vmcnt(33)
	v_pk_add_f32 v[78:79], v[78:79], v[234:235]
	v_pk_add_f32 v[76:77], v[76:77], v[232:233]
	s_waitcnt vmcnt(32)
	v_pk_add_f32 v[74:75], v[74:75], v[238:239]
	v_pk_add_f32 v[72:73], v[72:73], v[236:237]
	v_cvt_pk_bf16_f32 v82, v76, v77
	v_cvt_pk_bf16_f32 v83, v78, v79
	v_cvt_pk_bf16_f32 v84, v72, v73
	v_cvt_pk_bf16_f32 v85, v74, v75
	global_store_dwordx4 v[92:93], v[76:79], off
	global_store_dwordx4 v[92:93], v[72:75], off offset:16
	global_store_dwordx4 v[90:91], v[82:85], off
	global_load_dwordx4 v[232:235], v[174:175], off
	global_load_dwordx4 v[236:239], v[174:175], off offset:16
	s_nop 0
	v_mul_f32_e32 v77, v77, v77
	v_mul_f32_e32 v79, v79, v79
	v_mul_f32_e32 v73, v73, v73
	v_mul_f32_e32 v75, v75, v75
	v_fmac_f32_e32 v77, v76, v76
	v_fmac_f32_e32 v79, v78, v78
	v_fmac_f32_e32 v73, v72, v72
	v_fmac_f32_e32 v75, v74, v74
	v_add_f32_e32 v72, v77, v79
	v_add_f32_e32 v73, v73, v75
	v_add_f32_e32 v76, v72, v73
	s_waitcnt vmcnt(36)
	v_pk_add_f32 v[70:71], v[70:71], v[242:243]
	v_pk_add_f32 v[68:69], v[68:69], v[240:241]
	s_waitcnt vmcnt(35)
	v_pk_add_f32 v[74:75], v[66:67], v[246:247]
	v_pk_add_f32 v[72:73], v[64:65], v[244:245]
	v_mul_f32_e32 v64, v69, v69
	v_mul_f32_e32 v65, v71, v71
	v_mul_f32_e32 v66, v73, v73
	v_mul_f32_e32 v67, v75, v75
	v_fmac_f32_e32 v64, v68, v68
	v_fmac_f32_e32 v65, v70, v70
	v_fmac_f32_e32 v66, v72, v72
	v_fmac_f32_e32 v67, v74, v74
	v_add_f32_e32 v64, v64, v65
	v_add_f32_e32 v65, v66, v67
	v_add_f32_e32 v64, v64, v65
	v_add_f32_e32 v64, v76, v64
	ds_bpermute_b32 v65, v120, v64
	global_store_dwordx4 v[92:93], v[68:71], off offset:512
	global_store_dwordx4 v[92:93], v[72:75], off offset:528
	v_cvt_pk_bf16_f32 v66, v68, v69
	v_cvt_pk_bf16_f32 v67, v70, v71
	v_cvt_pk_bf16_f32 v68, v72, v73
	s_waitcnt lgkmcnt(0)
	v_add_f32_e32 v64, v64, v65
	ds_bpermute_b32 v65, v114, v64
	v_cvt_pk_bf16_f32 v69, v74, v75
	global_store_dwordx4 v[90:91], v[66:69], off offset:256
	s_and_saveexec_b64 s[24:25], s[2:3]
	s_cbranch_execz .LBB0_669
	v_readlane_b32 s26, v254, 41
	s_waitcnt lgkmcnt(0)
	v_add_f32_e32 v66, v64, v65
	v_lshlrev_b64 v[64:65], 6, v[80:81]
	v_readlane_b32 s27, v254, 42
	s_lshl_b32 s6, s38, 2
	s_nop 0
	v_lshl_add_u64 v[64:65], s[26:27], 0, v[64:65]
	v_lshl_add_u64 v[64:65], s[22:23], 2, v[64:65]
	v_lshl_add_u64 v[64:65], v[64:65], 0, s[6:7]
	global_store_dword v[64:65], v66, off
.LBB0_669:
	s_or_b64 exec, exec, s[24:25]
	v_add_u32_e32 v64, 0x80, v146
	s_waitcnt lgkmcnt(0)
	v_ashrrev_i32_e32 v65, 31, v64
	v_lshlrev_b64 v[66:67], 10, v[64:65]
	v_lshl_add_u64 v[74:75], v[66:67], 0, v[144:145]
	v_readlane_b32 s48, v254, 3
	v_lshlrev_b64 v[76:77], 2, v[74:75]
	v_readlane_b32 s49, v254, 4
	v_readlane_b32 s24, v254, 39
	v_readlane_b32 s25, v254, 40
	v_lshl_add_u64 v[78:79], s[48:49], 0, v[76:77]
	global_load_dwordx4 v[240:243], v[174:175], off offset:512
	global_load_dwordx4 v[244:247], v[174:175], off offset:528
	v_lshl_add_u64 v[74:75], v[74:75], 1, s[24:25]
	v_lshl_add_u64 v[76:77], s[68:69], 0, v[76:77]
	v_readlane_b32 s50, v254, 5
	v_readlane_b32 s51, v254, 6
	v_readlane_b32 s52, v254, 7
	v_readlane_b32 s53, v254, 8
	v_readlane_b32 s54, v254, 9
	v_readlane_b32 s55, v254, 10
	v_readlane_b32 s56, v254, 11
	v_readlane_b32 s57, v254, 12
	v_readlane_b32 s58, v254, 13
	v_readlane_b32 s59, v254, 14
	v_readlane_b32 s60, v254, 15
	v_readlane_b32 s61, v254, 16
	v_readlane_b32 s62, v254, 17
	v_readlane_b32 s63, v254, 18
	s_waitcnt vmcnt(36)
	v_pk_add_f32 v[62:63], v[62:63], v[178:179]
	v_pk_add_f32 v[60:61], v[60:61], v[176:177]
	s_waitcnt vmcnt(35)
	v_pk_add_f32 v[58:59], v[58:59], v[182:183]
	v_pk_add_f32 v[56:57], v[56:57], v[180:181]
	v_cvt_pk_bf16_f32 v66, v60, v61
	v_cvt_pk_bf16_f32 v67, v62, v63
	v_cvt_pk_bf16_f32 v68, v56, v57
	v_cvt_pk_bf16_f32 v69, v58, v59
	global_store_dwordx4 v[76:77], v[60:63], off
	global_store_dwordx4 v[76:77], v[56:59], off offset:16
	global_store_dwordx4 v[74:75], v[66:69], off
	s_nop 0
	v_mul_f32_e32 v61, v61, v61
	v_mul_f32_e32 v63, v63, v63
	v_mul_f32_e32 v57, v57, v57
	v_mul_f32_e32 v59, v59, v59
	v_fmac_f32_e32 v61, v60, v60
	v_fmac_f32_e32 v63, v62, v62
	v_fmac_f32_e32 v57, v56, v56
	v_fmac_f32_e32 v59, v58, v58
	v_add_f32_e32 v56, v61, v63
	v_add_f32_e32 v57, v57, v59
	v_add_f32_e32 v60, v56, v57
	s_waitcnt vmcnt(34)
	v_pk_add_f32 v[54:55], v[54:55], v[186:187]
	v_pk_add_f32 v[52:53], v[52:53], v[184:185]
	s_waitcnt vmcnt(33)
	v_pk_add_f32 v[58:59], v[50:51], v[190:191]
	v_pk_add_f32 v[56:57], v[48:49], v[188:189]
	v_mul_f32_e32 v48, v53, v53
	v_mul_f32_e32 v49, v55, v55
	v_mul_f32_e32 v50, v57, v57
	v_mul_f32_e32 v51, v59, v59
	v_fmac_f32_e32 v48, v52, v52
	v_fmac_f32_e32 v49, v54, v54
	v_fmac_f32_e32 v50, v56, v56
	v_fmac_f32_e32 v51, v58, v58
	v_add_f32_e32 v48, v48, v49
	v_add_f32_e32 v49, v50, v51
	v_add_f32_e32 v48, v48, v49
	v_add_f32_e32 v48, v60, v48
	ds_bpermute_b32 v49, v120, v48
	global_store_dwordx4 v[76:77], v[52:55], off offset:512
	global_store_dwordx4 v[76:77], v[56:59], off offset:528
	v_cvt_pk_bf16_f32 v50, v52, v53
	v_cvt_pk_bf16_f32 v51, v54, v55
	v_cvt_pk_bf16_f32 v52, v56, v57
	s_waitcnt lgkmcnt(0)
	v_add_f32_e32 v48, v48, v49
	ds_bpermute_b32 v49, v114, v48
	v_cvt_pk_bf16_f32 v53, v58, v59
	global_store_dwordx4 v[74:75], v[50:53], off offset:256
	s_and_saveexec_b64 s[24:25], s[2:3]
	s_cbranch_execz .LBB0_671
; __device__ __forceinline__ unsigned cvt_pk_bf16(float lo, float hi) { const f32x2_t v = {lo, hi}; const bf16x2_t b = __builtin_convertvector(v, bf16x2_t); return __builtin_bit_cast(unsigned, b); }
;     __device__ __forceinline__ void operator()(const f32x4 (&acc)[2][2][4][2], const Unit& u, int wr, int wc, int fr, int fq, const PG8_LAS float*) const {
;     ...
;             for (int m = 0; m < 4; ++m) { const int row = row0 + ai * HALF + m * 16; const size_t off = (size_t)row * ldc + col0; float ss = 0.f;
; #pragma unroll
;                 for (int bj = 0; bj < 2; ++bj) {
;                     const f32x4 b0 = *(const f32x4*)(base + off + bj * HALF), b1 = *(const f32x4*)(base + off + bj * HALF + 4);
;                     const f32x4 v0 = b0 + acc[ai][bj][m][0], v1 = b1 + acc[ai][bj][m][1];
;                     *(f32x4*)(out + off + bj * HALF) = v0; *(f32x4*)(out + off + bj * HALF + 4) = v1;
;                     if (xb) { u32x4 w; w.x = cvt_pk_bf16(v0[0], v0[1]); w.y = cvt_pk_bf16(v0[2], v0[3]); w.z = cvt_pk_bf16(v1[0], v1[1]); w.w = cvt_pk_bf16(v1[2], v1[3]);
;                         *(u32x4*)(xb + off + bj * HALF) = w;
;                         ss += ((v0[0] * v0[0] + v0[1] * v0[1]) + (v0[2] * v0[2] + v0[3] * v0[3])) + ((v1[0] * v1[0] + v1[1] * v1[1]) + (v1[2] * v1[2] + v1[3] * v1[3])); } }
;                 if (xb) { ss += __shfl_xor(ss, 16); ss += __shfl_xor(ss, 32); if (fq == 0) ssq[(size_t)row * 16 + u.pn * 4 + wc] = ss; } }
	v_readlane_b32 s26, v254, 41
	s_waitcnt lgkmcnt(0)
	v_add_f32_e32 v50, v48, v49
	v_lshlrev_b64 v[48:49], 6, v[64:65]
	v_readlane_b32 s27, v254, 42
	s_lshl_b32 s6, s38, 2
	s_nop 0
	v_lshl_add_u64 v[48:49], s[26:27], 0, v[48:49]
	v_lshl_add_u64 v[48:49], s[22:23], 2, v[48:49]
	v_lshl_add_u64 v[48:49], v[48:49], 0, s[6:7]
	global_store_dword v[48:49], v50, off
.LBB0_671:
	s_or_b64 exec, exec, s[24:25]
	v_add_u32_e32 v48, 0x90, v146
	s_waitcnt lgkmcnt(0)
	v_ashrrev_i32_e32 v49, 31, v48
	v_lshlrev_b64 v[50:51], 10, v[48:49]
	v_lshl_add_u64 v[58:59], v[50:51], 0, v[144:145]
	v_readlane_b32 s48, v254, 3
	v_lshlrev_b64 v[60:61], 2, v[58:59]
	v_readlane_b32 s49, v254, 4
	v_readlane_b32 s24, v254, 39
	v_readlane_b32 s25, v254, 40
	v_lshl_add_u64 v[62:63], s[48:49], 0, v[60:61]
	v_lshl_add_u64 v[58:59], v[58:59], 1, s[24:25]
	v_lshl_add_u64 v[60:61], s[68:69], 0, v[60:61]
	v_readlane_b32 s50, v254, 5
	v_readlane_b32 s51, v254, 6
	v_readlane_b32 s52, v254, 7
	v_readlane_b32 s53, v254, 8
	v_readlane_b32 s54, v254, 9
	v_readlane_b32 s55, v254, 10
	v_readlane_b32 s56, v254, 11
	v_readlane_b32 s57, v254, 12
	v_readlane_b32 s58, v254, 13
	v_readlane_b32 s59, v254, 14
	v_readlane_b32 s60, v254, 15
	v_readlane_b32 s61, v254, 16
	v_readlane_b32 s62, v254, 17
	v_readlane_b32 s63, v254, 18
	s_waitcnt vmcnt(32)
	v_pk_add_f32 v[46:47], v[46:47], v[194:195]
	v_pk_add_f32 v[44:45], v[44:45], v[192:193]
	s_waitcnt vmcnt(31)
	v_pk_add_f32 v[42:43], v[42:43], v[198:199]
	v_pk_add_f32 v[40:41], v[40:41], v[196:197]
	v_cvt_pk_bf16_f32 v50, v44, v45
	v_cvt_pk_bf16_f32 v51, v46, v47
	v_cvt_pk_bf16_f32 v52, v40, v41
	v_cvt_pk_bf16_f32 v53, v42, v43
	global_store_dwordx4 v[60:61], v[44:47], off
	global_store_dwordx4 v[60:61], v[40:43], off offset:16
	global_store_dwordx4 v[58:59], v[50:53], off
	s_nop 0
	v_mul_f32_e32 v45, v45, v45
	v_mul_f32_e32 v47, v47, v47
	v_mul_f32_e32 v41, v41, v41
	v_mul_f32_e32 v43, v43, v43
	v_fmac_f32_e32 v45, v44, v44
	v_fmac_f32_e32 v47, v46, v46
	v_fmac_f32_e32 v41, v40, v40
	v_fmac_f32_e32 v43, v42, v42
	v_add_f32_e32 v40, v45, v47
	v_add_f32_e32 v41, v41, v43
	v_add_f32_e32 v44, v40, v41
	s_waitcnt vmcnt(30)
	v_pk_add_f32 v[38:39], v[38:39], v[202:203]
	v_pk_add_f32 v[36:37], v[36:37], v[200:201]
	s_waitcnt vmcnt(29)
	v_pk_add_f32 v[42:43], v[34:35], v[206:207]
	v_pk_add_f32 v[40:41], v[32:33], v[204:205]
	v_mul_f32_e32 v32, v37, v37
	v_mul_f32_e32 v33, v39, v39
	v_mul_f32_e32 v34, v41, v41
	v_mul_f32_e32 v35, v43, v43
	v_fmac_f32_e32 v32, v36, v36
	v_fmac_f32_e32 v33, v38, v38
	v_fmac_f32_e32 v34, v40, v40
	v_fmac_f32_e32 v35, v42, v42
	v_add_f32_e32 v32, v32, v33
	v_add_f32_e32 v33, v34, v35
	v_add_f32_e32 v32, v32, v33
	v_add_f32_e32 v32, v44, v32
	ds_bpermute_b32 v33, v120, v32
	global_store_dwordx4 v[60:61], v[36:39], off offset:512
	global_store_dwordx4 v[60:61], v[40:43], off offset:528
	v_cvt_pk_bf16_f32 v34, v36, v37
	v_cvt_pk_bf16_f32 v35, v38, v39
	v_cvt_pk_bf16_f32 v36, v40, v41
	s_waitcnt lgkmcnt(0)
	v_add_f32_e32 v32, v32, v33
	ds_bpermute_b32 v33, v114, v32
	v_cvt_pk_bf16_f32 v37, v42, v43
	global_store_dwordx4 v[58:59], v[34:37], off offset:256
	s_and_saveexec_b64 s[24:25], s[2:3]
	s_cbranch_execz .LBB0_673
	v_readlane_b32 s26, v254, 41
	s_waitcnt lgkmcnt(0)
	v_add_f32_e32 v34, v32, v33
	v_lshlrev_b64 v[32:33], 6, v[48:49]
	v_readlane_b32 s27, v254, 42
	s_lshl_b32 s6, s38, 2
	s_nop 0
	v_lshl_add_u64 v[32:33], s[26:27], 0, v[32:33]
	v_lshl_add_u64 v[32:33], s[22:23], 2, v[32:33]
	v_lshl_add_u64 v[32:33], v[32:33], 0, s[6:7]
	global_store_dword v[32:33], v34, off
; __device__ __forceinline__ unsigned cvt_pk_bf16(float lo, float hi) { const f32x2_t v = {lo, hi}; const bf16x2_t b = __builtin_convertvector(v, bf16x2_t); return __builtin_bit_cast(unsigned, b); }
;     __device__ __forceinline__ void operator()(const f32x4 (&acc)[2][2][4][2], const Unit& u, int wr, int wc, int fr, int fq, const PG8_LAS float*) const {
;     ...
;             for (int m = 0; m < 4; ++m) { const int row = row0 + ai * HALF + m * 16; const size_t off = (size_t)row * ldc + col0; float ss = 0.f;
; #pragma unroll
;                 for (int bj = 0; bj < 2; ++bj) {
;                     const f32x4 b0 = *(const f32x4*)(base + off + bj * HALF), b1 = *(const f32x4*)(base + off + bj * HALF + 4);
;                     const f32x4 v0 = b0 + acc[ai][bj][m][0], v1 = b1 + acc[ai][bj][m][1];
;                     *(f32x4*)(out + off + bj * HALF) = v0; *(f32x4*)(out + off + bj * HALF + 4) = v1;
;                     if (xb) { u32x4 w; w.x = cvt_pk_bf16(v0[0], v0[1]); w.y = cvt_pk_bf16(v0[2], v0[3]); w.z = cvt_pk_bf16(v1[0], v1[1]); w.w = cvt_pk_bf16(v1[2], v1[3]);
;                         *(u32x4*)(xb + off + bj * HALF) = w;
;                         ss += ((v0[0] * v0[0] + v0[1] * v0[1]) + (v0[2] * v0[2] + v0[3] * v0[3])) + ((v1[0] * v1[0] + v1[1] * v1[1]) + (v1[2] * v1[2] + v1[3] * v1[3])); } }
;                 if (xb) { ss += __shfl_xor(ss, 16); ss += __shfl_xor(ss, 32); if (fq == 0) ssq[(size_t)row * 16 + u.pn * 4 + wc] = ss; } }
.LBB0_673:
	s_or_b64 exec, exec, s[24:25]
	v_add_u32_e32 v32, 0xa0, v146
	s_waitcnt lgkmcnt(0)
	v_ashrrev_i32_e32 v33, 31, v32
	v_lshlrev_b64 v[34:35], 10, v[32:33]
	v_lshl_add_u64 v[42:43], v[34:35], 0, v[144:145]
	v_readlane_b32 s48, v254, 3
	v_lshlrev_b64 v[44:45], 2, v[42:43]
	v_readlane_b32 s49, v254, 4
	v_readlane_b32 s24, v254, 39
	v_readlane_b32 s25, v254, 40
	v_lshl_add_u64 v[46:47], s[48:49], 0, v[44:45]
	v_lshl_add_u64 v[42:43], v[42:43], 1, s[24:25]
	v_lshl_add_u64 v[44:45], s[68:69], 0, v[44:45]
	v_readlane_b32 s50, v254, 5
	v_readlane_b32 s51, v254, 6
	v_readlane_b32 s52, v254, 7
	v_readlane_b32 s53, v254, 8
	v_readlane_b32 s54, v254, 9
	v_readlane_b32 s55, v254, 10
	v_readlane_b32 s56, v254, 11
	v_readlane_b32 s57, v254, 12
	v_readlane_b32 s58, v254, 13
	v_readlane_b32 s59, v254, 14
	v_readlane_b32 s60, v254, 15
	v_readlane_b32 s61, v254, 16
	v_readlane_b32 s62, v254, 17
	v_readlane_b32 s63, v254, 18
	s_waitcnt vmcnt(28)
	v_pk_add_f32 v[30:31], v[30:31], v[210:211]
	v_pk_add_f32 v[28:29], v[28:29], v[208:209]
	s_waitcnt vmcnt(27)
	v_pk_add_f32 v[26:27], v[26:27], v[214:215]
	v_pk_add_f32 v[24:25], v[24:25], v[212:213]
	v_cvt_pk_bf16_f32 v34, v28, v29
	v_cvt_pk_bf16_f32 v35, v30, v31
	v_cvt_pk_bf16_f32 v36, v24, v25
	v_cvt_pk_bf16_f32 v37, v26, v27
	global_store_dwordx4 v[44:45], v[28:31], off
	global_store_dwordx4 v[44:45], v[24:27], off offset:16
	global_store_dwordx4 v[42:43], v[34:37], off
	s_nop 0
	v_mul_f32_e32 v29, v29, v29
	v_mul_f32_e32 v31, v31, v31
	v_mul_f32_e32 v25, v25, v25
	v_mul_f32_e32 v27, v27, v27
	v_fmac_f32_e32 v29, v28, v28
	v_fmac_f32_e32 v31, v30, v30
	v_fmac_f32_e32 v25, v24, v24
	v_fmac_f32_e32 v27, v26, v26
	v_add_f32_e32 v24, v29, v31
	v_add_f32_e32 v25, v25, v27
	v_add_f32_e32 v28, v24, v25
	s_waitcnt vmcnt(26)
	v_pk_add_f32 v[22:23], v[22:23], v[218:219]
	v_pk_add_f32 v[20:21], v[20:21], v[216:217]
	s_waitcnt vmcnt(25)
	v_pk_add_f32 v[26:27], v[18:19], v[230:231]
	v_pk_add_f32 v[24:25], v[16:17], v[228:229]
	v_mul_f32_e32 v16, v21, v21
	v_mul_f32_e32 v17, v23, v23
	v_mul_f32_e32 v18, v25, v25
	v_mul_f32_e32 v19, v27, v27
	v_fmac_f32_e32 v16, v20, v20
	v_fmac_f32_e32 v17, v22, v22
	v_fmac_f32_e32 v18, v24, v24
	v_fmac_f32_e32 v19, v26, v26
	v_add_f32_e32 v16, v16, v17
	v_add_f32_e32 v17, v18, v19
	v_add_f32_e32 v16, v16, v17
	v_add_f32_e32 v16, v28, v16
	ds_bpermute_b32 v17, v120, v16
	global_store_dwordx4 v[44:45], v[20:23], off offset:512
	global_store_dwordx4 v[44:45], v[24:27], off offset:528
	v_cvt_pk_bf16_f32 v18, v20, v21
	v_cvt_pk_bf16_f32 v19, v22, v23
	v_cvt_pk_bf16_f32 v20, v24, v25
	s_waitcnt lgkmcnt(0)
	v_add_f32_e32 v16, v16, v17
	ds_bpermute_b32 v17, v114, v16
	v_cvt_pk_bf16_f32 v21, v26, v27
	global_store_dwordx4 v[42:43], v[18:21], off offset:256
	s_and_saveexec_b64 s[24:25], s[2:3]
	s_cbranch_execz .LBB0_675
	v_readlane_b32 s26, v254, 41
	s_waitcnt lgkmcnt(0)
	v_add_f32_e32 v18, v16, v17
	v_lshlrev_b64 v[16:17], 6, v[32:33]
	v_readlane_b32 s27, v254, 42
	s_lshl_b32 s6, s38, 2
	s_nop 0
	v_lshl_add_u64 v[16:17], s[26:27], 0, v[16:17]
	v_lshl_add_u64 v[16:17], s[22:23], 2, v[16:17]
	v_lshl_add_u64 v[16:17], v[16:17], 0, s[6:7]
	global_store_dword v[16:17], v18, off
.LBB0_675:
	s_or_b64 exec, exec, s[24:25]
	v_add_u32_e32 v16, 0xb0, v146
	s_waitcnt lgkmcnt(0)
	v_ashrrev_i32_e32 v17, 31, v16
	v_lshlrev_b64 v[18:19], 10, v[16:17]
	v_lshl_add_u64 v[26:27], v[18:19], 0, v[144:145]
	v_readlane_b32 s48, v254, 3
	v_lshlrev_b64 v[28:29], 2, v[26:27]
	v_readlane_b32 s49, v254, 4
	v_readlane_b32 s24, v254, 39
	v_readlane_b32 s25, v254, 40
	v_lshl_add_u64 v[30:31], s[48:49], 0, v[28:29]
	v_lshl_add_u64 v[26:27], v[26:27], 1, s[24:25]
	v_lshl_add_u64 v[28:29], s[68:69], 0, v[28:29]
	v_readlane_b32 s50, v254, 5
	v_readlane_b32 s51, v254, 6
	v_readlane_b32 s52, v254, 7
	v_readlane_b32 s53, v254, 8
	v_readlane_b32 s54, v254, 9
	v_readlane_b32 s55, v254, 10
	v_readlane_b32 s56, v254, 11
	v_readlane_b32 s57, v254, 12
	v_readlane_b32 s58, v254, 13
	v_readlane_b32 s59, v254, 14
	v_readlane_b32 s60, v254, 15
	v_readlane_b32 s61, v254, 16
	v_readlane_b32 s62, v254, 17
	v_readlane_b32 s63, v254, 18
	s_waitcnt vmcnt(24)
	v_pk_add_f32 v[14:15], v[14:15], v[234:235]
	v_pk_add_f32 v[12:13], v[12:13], v[232:233]
	s_waitcnt vmcnt(23)
	v_pk_add_f32 v[10:11], v[10:11], v[238:239]
	v_pk_add_f32 v[8:9], v[8:9], v[236:237]
	v_cvt_pk_bf16_f32 v18, v12, v13
	v_cvt_pk_bf16_f32 v19, v14, v15
	v_cvt_pk_bf16_f32 v20, v8, v9
	v_cvt_pk_bf16_f32 v21, v10, v11
	global_store_dwordx4 v[28:29], v[12:15], off
	global_store_dwordx4 v[28:29], v[8:11], off offset:16
	global_store_dwordx4 v[26:27], v[18:21], off
	s_nop 0
	v_mul_f32_e32 v13, v13, v13
	v_mul_f32_e32 v15, v15, v15
	v_mul_f32_e32 v9, v9, v9
	v_mul_f32_e32 v11, v11, v11
	v_fmac_f32_e32 v13, v12, v12
	v_fmac_f32_e32 v15, v14, v14
	v_fmac_f32_e32 v9, v8, v8
	v_fmac_f32_e32 v11, v10, v10
	v_add_f32_e32 v8, v13, v15
	v_add_f32_e32 v9, v9, v11
	v_add_f32_e32 v12, v8, v9
	s_waitcnt vmcnt(22)
	v_pk_add_f32 v[6:7], v[6:7], v[242:243]
	v_pk_add_f32 v[4:5], v[4:5], v[240:241]
	s_waitcnt vmcnt(21)
	v_pk_add_f32 v[10:11], v[2:3], v[246:247]
	v_pk_add_f32 v[8:9], v[0:1], v[244:245]
	v_mul_f32_e32 v0, v5, v5
	v_mul_f32_e32 v1, v7, v7
	v_mul_f32_e32 v2, v9, v9
	v_mul_f32_e32 v3, v11, v11
	v_fmac_f32_e32 v0, v4, v4
	v_fmac_f32_e32 v1, v6, v6
	v_fmac_f32_e32 v2, v8, v8
	v_fmac_f32_e32 v3, v10, v10
	v_add_f32_e32 v0, v0, v1
	v_add_f32_e32 v1, v2, v3
	v_add_f32_e32 v0, v0, v1
	v_add_f32_e32 v0, v12, v0
	ds_bpermute_b32 v1, v120, v0
	global_store_dwordx4 v[28:29], v[4:7], off offset:512
	global_store_dwordx4 v[28:29], v[8:11], off offset:528
	v_cvt_pk_bf16_f32 v2, v4, v5
	v_cvt_pk_bf16_f32 v3, v6, v7
	v_cvt_pk_bf16_f32 v4, v8, v9
	s_waitcnt lgkmcnt(0)
	v_add_f32_e32 v0, v0, v1
	ds_bpermute_b32 v1, v114, v0
	v_cvt_pk_bf16_f32 v5, v10, v11
	global_store_dwordx4 v[26:27], v[2:5], off offset:256
	s_and_saveexec_b64 s[24:25], s[2:3]
	s_cbranch_execz .LBB0_677
	v_readlane_b32 s26, v254, 41
	s_waitcnt lgkmcnt(0)
	v_add_f32_e32 v2, v0, v1
	v_lshlrev_b64 v[0:1], 6, v[16:17]
	v_readlane_b32 s27, v254, 42
	s_lshl_b32 s6, s38, 2
	s_nop 0
	v_lshl_add_u64 v[0:1], s[26:27], 0, v[0:1]
	v_lshl_add_u64 v[0:1], s[22:23], 2, v[0:1]
	v_lshl_add_u64 v[0:1], v[0:1], 0, s[6:7]
	global_store_dword v[0:1], v2, off

; #define PG8_LAS __attribute__((address_space(3)))
; __device__ __forceinline__ unsigned cvt_pk_bf16(float lo, float hi) { const f32x2_t v = {lo, hi}; const bf16x2_t b = __builtin_convertvector(v, bf16x2_t); return __builtin_bit_cast(unsigned, b); }
;     __device__ __forceinline__ void operator()(const f32x4 (&acc)[2][2][4][2], const Unit& u, int wr, int wc, int fr, int fq, const PG8_LAS float*) const {
;         const int row0 = u.pm * BM + wr * 64 + fr; const int col0 = u.pn * BM + wc * 32 + 8 * fq;
; #pragma unroll
;         for (int ai = 0; ai < 2; ++ai)
; #pragma unroll
;             for (int m = 0; m < 4; ++m) { const int row = row0 + ai * HALF + m * 16; const size_t off = (size_t)row * ldc + col0; float ss = 0.f;
; #pragma unroll
;                 for (int bj = 0; bj < 2; ++bj) {
;                     const f32x4 b0 = *(const f32x4*)(base + off + bj * HALF), b1 = *(const f32x4*)(base + off + bj * HALF + 4);
;                     const f32x4 v0 = b0 + acc[ai][bj][m][0], v1 = b1 + acc[ai][bj][m][1];
;                     *(f32x4*)(out + off + bj * HALF) = v0; *(f32x4*)(out + off + bj * HALF + 4) = v1;
;                     if (xb) { u32x4 w; w.x = cvt_pk_bf16(v0[0], v0[1]); w.y = cvt_pk_bf16(v0[2], v0[3]); w.z = cvt_pk_bf16(v1[0], v1[1]); w.w = cvt_pk_bf16(v1[2], v1[3]);
;                         *(u32x4*)(xb + off + bj * HALF) = w;
;                         ss += ((v0[0] * v0[0] + v0[1] * v0[1]) + (v0[2] * v0[2] + v0[3] * v0[3])) + ((v1[0] * v1[0] + v1[1] * v1[1]) + (v1[2] * v1[2] + v1[3] * v1[3])); } }
;                 if (xb) { ss += __shfl_xor(ss, 16); ss += __shfl_xor(ss, 32); if (fq == 0) ssq[(size_t)row * 16 + u.pn * 4 + wc] = ss; } }
.LBB0_845:
	v_lshl_add_u32 v146, s22, 8, v148
	v_lshl_or_b32 v144, s6, 8, v150
	v_ashrrev_i32_e32 v147, 31, v146
	v_ashrrev_i32_e32 v145, 31, v144
	v_lshlrev_b64 v[156:157], 10, v[146:147]
	v_lshl_add_u64 v[164:165], v[156:157], 0, v[144:145]
	v_lshl_add_u64 v[172:173], v[164:165], 2, s[68:69]
	v_mov_b32_e32 v174, v172
	v_mov_b32_e32 v175, v173
	s_mov_b64 s[98:99], 0x10000
	s_mov_b64 s[100:101], 0x50000
	global_load_dwordx4 v[176:179], v[174:175], off
	global_load_dwordx4 v[180:183], v[174:175], off offset:16
	global_load_dwordx4 v[184:187], v[174:175], off offset:512
	global_load_dwordx4 v[188:191], v[174:175], off offset:528
	v_lshl_add_u64 v[174:175], v[174:175], 0, s[98:99]
	global_load_dwordx4 v[192:195], v[174:175], off
	global_load_dwordx4 v[196:199], v[174:175], off offset:16
	global_load_dwordx4 v[200:203], v[174:175], off offset:512
	global_load_dwordx4 v[204:207], v[174:175], off offset:528
	v_lshl_add_u64 v[174:175], v[174:175], 0, s[98:99]
	global_load_dwordx4 v[208:211], v[174:175], off
	global_load_dwordx4 v[212:215], v[174:175], off offset:16
	global_load_dwordx4 v[216:219], v[174:175], off offset:512
	global_load_dwordx4 v[228:231], v[174:175], off offset:528
	v_lshl_add_u64 v[174:175], v[174:175], 0, s[98:99]
	global_load_dwordx4 v[232:235], v[174:175], off
	global_load_dwordx4 v[236:239], v[174:175], off offset:16
	global_load_dwordx4 v[240:243], v[174:175], off offset:512
	global_load_dwordx4 v[244:247], v[174:175], off offset:528
	v_lshl_add_u64 v[174:175], v[174:175], 0, s[100:101]
	v_readlane_b32 s22, v254, 39
	v_readlane_b32 s23, v254, 40
	v_xor_b32_e32 v155, 32, v154
	s_waitcnt vmcnt(14)
	v_pk_add_f32 v[126:127], v[126:127], v[178:179]
	v_pk_add_f32 v[124:125], v[124:125], v[176:177]
	v_pk_add_f32 v[158:159], v[122:123], v[182:183]
	v_pk_add_f32 v[156:157], v[120:121], v[180:181]
	v_lshl_add_u64 v[164:165], v[164:165], 1, s[22:23]
	v_cvt_pk_bf16_f32 v120, v124, v125
	v_cvt_pk_bf16_f32 v121, v126, v127
	v_cvt_pk_bf16_f32 v122, v156, v157
	v_cvt_pk_bf16_f32 v123, v158, v159
	global_store_dwordx4 v[172:173], v[124:127], off
	global_store_dwordx4 v[172:173], v[156:159], off offset:16
	global_store_dwordx4 v[164:165], v[120:123], off
	global_load_dwordx4 v[176:179], v[174:175], off
	global_load_dwordx4 v[180:183], v[174:175], off offset:16
	v_mul_f32_e32 v122, v125, v125
	v_mul_f32_e32 v123, v127, v127
	v_mul_f32_e32 v125, v157, v157
	v_mul_f32_e32 v127, v159, v159
	v_fmac_f32_e32 v122, v124, v124
	v_fmac_f32_e32 v123, v126, v126
	v_fmac_f32_e32 v125, v156, v156
	v_fmac_f32_e32 v127, v158, v158
	v_add_f32_e32 v122, v122, v123
	v_add_f32_e32 v123, v125, v127
	v_add_f32_e32 v126, v122, v123
	v_and_b32_e32 v121, 64, v154
	v_xor_b32_e32 v120, 16, v154
	v_add_u32_e32 v121, 64, v121
	v_cmp_lt_i32_e32 vcc, v120, v121
	s_lshl_b32 s22, s6, 2
	s_ashr_i32 s23, s22, 31
	v_cndmask_b32_e32 v120, v154, v120, vcc
	v_lshlrev_b32_e32 v120, 2, v120
	v_cmp_lt_i32_e32 vcc, v155, v121
	s_waitcnt vmcnt(18)
	v_pk_add_f32 v[118:119], v[118:119], v[186:187]
	v_pk_add_f32 v[116:117], v[116:117], v[184:185]
	s_waitcnt vmcnt(17)
	v_pk_add_f32 v[124:125], v[114:115], v[190:191]
	v_pk_add_f32 v[122:123], v[112:113], v[188:189]
	v_mul_f32_e32 v112, v117, v117
	v_mul_f32_e32 v113, v119, v119
	v_mul_f32_e32 v114, v123, v123
	v_mul_f32_e32 v115, v125, v125
	v_fmac_f32_e32 v112, v116, v116
	v_fmac_f32_e32 v113, v118, v118
	v_fmac_f32_e32 v114, v122, v122
	v_fmac_f32_e32 v115, v124, v124
	v_add_f32_e32 v112, v112, v113
	v_add_f32_e32 v113, v114, v115
	v_add_f32_e32 v112, v112, v113
	v_add_f32_e32 v112, v126, v112
	ds_bpermute_b32 v113, v120, v112
	v_cndmask_b32_e32 v114, v154, v155, vcc
	v_lshlrev_b32_e32 v114, 2, v114
	global_store_dwordx4 v[172:173], v[116:119], off offset:512
	global_store_dwordx4 v[172:173], v[122:125], off offset:528
	s_waitcnt lgkmcnt(0)
	v_add_f32_e32 v112, v112, v113
	ds_bpermute_b32 v113, v114, v112
	v_cvt_pk_bf16_f32 v116, v116, v117
	v_cvt_pk_bf16_f32 v117, v118, v119
	v_cvt_pk_bf16_f32 v118, v122, v123
	v_cvt_pk_bf16_f32 v119, v124, v125
	global_store_dwordx4 v[164:165], v[116:119], off offset:256
	s_and_saveexec_b64 s[24:25], s[2:3]
	s_cbranch_execz .LBB0_847
	v_readlane_b32 s26, v254, 41
	s_waitcnt lgkmcnt(0)
	v_add_f32_e32 v115, v112, v113
	v_lshlrev_b64 v[112:113], 6, v[146:147]
	v_readlane_b32 s27, v254, 42
	s_lshl_b32 s6, s38, 2
	s_nop 0
	v_lshl_add_u64 v[112:113], s[26:27], 0, v[112:113]
	v_lshl_add_u64 v[112:113], s[22:23], 2, v[112:113]
	v_lshl_add_u64 v[112:113], v[112:113], 0, s[6:7]
	global_store_dword v[112:113], v115, off
; __device__ __forceinline__ unsigned cvt_pk_bf16(float lo, float hi) { const f32x2_t v = {lo, hi}; const bf16x2_t b = __builtin_convertvector(v, bf16x2_t); return __builtin_bit_cast(unsigned, b); }
;     __device__ __forceinline__ void operator()(const f32x4 (&acc)[2][2][4][2], const Unit& u, int wr, int wc, int fr, int fq, const PG8_LAS float*) const {
;     ...
;             for (int m = 0; m < 4; ++m) { const int row = row0 + ai * HALF + m * 16; const size_t off = (size_t)row * ldc + col0; float ss = 0.f;
; #pragma unroll
;                 for (int bj = 0; bj < 2; ++bj) {
;                     const f32x4 b0 = *(const f32x4*)(base + off + bj * HALF), b1 = *(const f32x4*)(base + off + bj * HALF + 4);
;                     const f32x4 v0 = b0 + acc[ai][bj][m][0], v1 = b1 + acc[ai][bj][m][1];
;                     *(f32x4*)(out + off + bj * HALF) = v0; *(f32x4*)(out + off + bj * HALF + 4) = v1;
;                     if (xb) { u32x4 w; w.x = cvt_pk_bf16(v0[0], v0[1]); w.y = cvt_pk_bf16(v0[2], v0[3]); w.z = cvt_pk_bf16(v1[0], v1[1]); w.w = cvt_pk_bf16(v1[2], v1[3]);
;                         *(u32x4*)(xb + off + bj * HALF) = w;
;                         ss += ((v0[0] * v0[0] + v0[1] * v0[1]) + (v0[2] * v0[2] + v0[3] * v0[3])) + ((v1[0] * v1[0] + v1[1] * v1[1]) + (v1[2] * v1[2] + v1[3] * v1[3])); } }
;                 if (xb) { ss += __shfl_xor(ss, 16); ss += __shfl_xor(ss, 32); if (fq == 0) ssq[(size_t)row * 16 + u.pn * 4 + wc] = ss; } }
.LBB0_847:
	s_or_b64 exec, exec, s[24:25]
	v_or_b32_e32 v112, 16, v146
	s_waitcnt lgkmcnt(0)
	v_ashrrev_i32_e32 v113, 31, v112
	v_lshlrev_b64 v[116:117], 10, v[112:113]
	v_lshl_add_u64 v[126:127], v[116:117], 0, v[144:145]
	v_lshl_add_u64 v[156:157], v[126:127], 2, s[68:69]
	global_load_dwordx4 v[184:187], v[174:175], off offset:512
	global_load_dwordx4 v[188:191], v[174:175], off offset:528
	v_lshl_add_u64 v[174:175], v[174:175], 0, s[98:99]
	v_readlane_b32 s24, v254, 39
	v_readlane_b32 s25, v254, 40
	s_waitcnt vmcnt(21)
	v_pk_add_f32 v[110:111], v[110:111], v[194:195]
	v_pk_add_f32 v[108:109], v[108:109], v[192:193]
	s_waitcnt vmcnt(20)
	v_pk_add_f32 v[106:107], v[106:107], v[198:199]
	v_pk_add_f32 v[104:105], v[104:105], v[196:197]
	v_lshl_add_u64 v[126:127], v[126:127], 1, s[24:25]
	v_cvt_pk_bf16_f32 v116, v108, v109
	v_cvt_pk_bf16_f32 v117, v110, v111
	v_cvt_pk_bf16_f32 v118, v104, v105
	v_cvt_pk_bf16_f32 v119, v106, v107
	global_store_dwordx4 v[156:157], v[108:111], off
	global_store_dwordx4 v[156:157], v[104:107], off offset:16
	global_store_dwordx4 v[126:127], v[116:119], off
	global_load_dwordx4 v[192:195], v[174:175], off
	global_load_dwordx4 v[196:199], v[174:175], off offset:16
	s_nop 0
	v_mul_f32_e32 v109, v109, v109
	v_mul_f32_e32 v111, v111, v111
	v_mul_f32_e32 v105, v105, v105
	v_mul_f32_e32 v107, v107, v107
	v_fmac_f32_e32 v109, v108, v108
	v_fmac_f32_e32 v111, v110, v110
	v_fmac_f32_e32 v105, v104, v104
	v_fmac_f32_e32 v107, v106, v106
	v_add_f32_e32 v104, v109, v111
	v_add_f32_e32 v105, v105, v107
	v_add_f32_e32 v108, v104, v105
	s_waitcnt vmcnt(24)
	v_pk_add_f32 v[102:103], v[102:103], v[202:203]
	v_pk_add_f32 v[100:101], v[100:101], v[200:201]
	s_waitcnt vmcnt(23)
	v_pk_add_f32 v[106:107], v[98:99], v[206:207]
	v_pk_add_f32 v[104:105], v[96:97], v[204:205]
	v_mul_f32_e32 v96, v101, v101
	v_mul_f32_e32 v97, v103, v103
	v_mul_f32_e32 v98, v105, v105
	v_mul_f32_e32 v99, v107, v107
	v_fmac_f32_e32 v96, v100, v100
	v_fmac_f32_e32 v97, v102, v102
	v_fmac_f32_e32 v98, v104, v104
	v_fmac_f32_e32 v99, v106, v106
	v_add_f32_e32 v96, v96, v97
	v_add_f32_e32 v97, v98, v99
	v_add_f32_e32 v96, v96, v97
	v_add_f32_e32 v96, v108, v96
	ds_bpermute_b32 v97, v120, v96
	global_store_dwordx4 v[156:157], v[100:103], off offset:512
	global_store_dwordx4 v[156:157], v[104:107], off offset:528
	v_cvt_pk_bf16_f32 v98, v100, v101
	v_cvt_pk_bf16_f32 v99, v102, v103
	v_cvt_pk_bf16_f32 v100, v104, v105
	s_waitcnt lgkmcnt(0)
	v_add_f32_e32 v96, v96, v97
	ds_bpermute_b32 v97, v114, v96
	v_cvt_pk_bf16_f32 v101, v106, v107
	global_store_dwordx4 v[126:127], v[98:101], off offset:256
	s_and_saveexec_b64 s[24:25], s[2:3]
	s_cbranch_execz .LBB0_849
	v_readlane_b32 s26, v254, 41
	s_waitcnt lgkmcnt(0)
	v_add_f32_e32 v98, v96, v97
	v_lshlrev_b64 v[96:97], 6, v[112:113]
	v_readlane_b32 s27, v254, 42
	s_lshl_b32 s6, s38, 2
	s_nop 0
	v_lshl_add_u64 v[96:97], s[26:27], 0, v[96:97]
	v_lshl_add_u64 v[96:97], s[22:23], 2, v[96:97]
	v_lshl_add_u64 v[96:97], v[96:97], 0, s[6:7]
	global_store_dword v[96:97], v98, off
.LBB0_849:
	s_or_b64 exec, exec, s[24:25]
	v_or_b32_e32 v96, 32, v146
	s_waitcnt lgkmcnt(0)
	v_ashrrev_i32_e32 v97, 31, v96
	v_lshlrev_b64 v[98:99], 10, v[96:97]
	v_lshl_add_u64 v[106:107], v[98:99], 0, v[144:145]
	v_lshl_add_u64 v[108:109], v[106:107], 2, s[68:69]
	global_load_dwordx4 v[200:203], v[174:175], off offset:512
	global_load_dwordx4 v[204:207], v[174:175], off offset:528
	v_lshl_add_u64 v[174:175], v[174:175], 0, s[98:99]
	v_readlane_b32 s24, v254, 39
	v_readlane_b32 s25, v254, 40
	s_waitcnt vmcnt(27)
	v_pk_add_f32 v[94:95], v[94:95], v[210:211]
	v_pk_add_f32 v[92:93], v[92:93], v[208:209]
	s_waitcnt vmcnt(26)
	v_pk_add_f32 v[90:91], v[90:91], v[214:215]
	v_pk_add_f32 v[88:89], v[88:89], v[212:213]
	v_lshl_add_u64 v[106:107], v[106:107], 1, s[24:25]
	v_cvt_pk_bf16_f32 v98, v92, v93
	v_cvt_pk_bf16_f32 v99, v94, v95
	v_cvt_pk_bf16_f32 v100, v88, v89
	v_cvt_pk_bf16_f32 v101, v90, v91
	global_store_dwordx4 v[108:109], v[92:95], off
	global_store_dwordx4 v[108:109], v[88:91], off offset:16
	global_store_dwordx4 v[106:107], v[98:101], off
	global_load_dwordx4 v[208:211], v[174:175], off
	global_load_dwordx4 v[212:215], v[174:175], off offset:16
	s_nop 0
	v_mul_f32_e32 v93, v93, v93
	v_mul_f32_e32 v95, v95, v95
	v_mul_f32_e32 v89, v89, v89
	v_mul_f32_e32 v91, v91, v91
	v_fmac_f32_e32 v93, v92, v92
	v_fmac_f32_e32 v95, v94, v94
	v_fmac_f32_e32 v89, v88, v88
	v_fmac_f32_e32 v91, v90, v90
	v_add_f32_e32 v88, v93, v95
	v_add_f32_e32 v89, v89, v91
	v_add_f32_e32 v92, v88, v89
	s_waitcnt vmcnt(30)
	v_pk_add_f32 v[86:87], v[86:87], v[218:219]
	v_pk_add_f32 v[84:85], v[84:85], v[216:217]
	s_waitcnt vmcnt(29)
	v_pk_add_f32 v[90:91], v[82:83], v[230:231]
	v_pk_add_f32 v[88:89], v[80:81], v[228:229]
	v_mul_f32_e32 v80, v85, v85
	v_mul_f32_e32 v81, v87, v87
	v_mul_f32_e32 v82, v89, v89
	v_mul_f32_e32 v83, v91, v91
	v_fmac_f32_e32 v80, v84, v84
	v_fmac_f32_e32 v81, v86, v86
	v_fmac_f32_e32 v82, v88, v88
	v_fmac_f32_e32 v83, v90, v90
	v_add_f32_e32 v80, v80, v81
	v_add_f32_e32 v81, v82, v83
	v_add_f32_e32 v80, v80, v81
	v_add_f32_e32 v80, v92, v80
	ds_bpermute_b32 v81, v120, v80
	global_store_dwordx4 v[108:109], v[84:87], off offset:512
	global_store_dwordx4 v[108:109], v[88:91], off offset:528
	v_cvt_pk_bf16_f32 v82, v84, v85
	v_cvt_pk_bf16_f32 v83, v86, v87
	v_cvt_pk_bf16_f32 v84, v88, v89
	s_waitcnt lgkmcnt(0)
	v_add_f32_e32 v80, v80, v81
	ds_bpermute_b32 v81, v114, v80
	v_cvt_pk_bf16_f32 v85, v90, v91
	global_store_dwordx4 v[106:107], v[82:85], off offset:256
	s_and_saveexec_b64 s[24:25], s[2:3]
	s_cbranch_execz .LBB0_851
	v_readlane_b32 s26, v254, 41
	s_waitcnt lgkmcnt(0)
	v_add_f32_e32 v82, v80, v81
	v_lshlrev_b64 v[80:81], 6, v[96:97]
	v_readlane_b32 s27, v254, 42
	s_lshl_b32 s6, s38, 2
	s_nop 0
	v_lshl_add_u64 v[80:81], s[26:27], 0, v[80:81]
	v_lshl_add_u64 v[80:81], s[22:23], 2, v[80:81]
	v_lshl_add_u64 v[80:81], v[80:81], 0, s[6:7]
	global_store_dword v[80:81], v82, off
; __device__ __forceinline__ unsigned cvt_pk_bf16(float lo, float hi) { const f32x2_t v = {lo, hi}; const bf16x2_t b = __builtin_convertvector(v, bf16x2_t); return __builtin_bit_cast(unsigned, b); }
;     __device__ __forceinline__ void operator()(const f32x4 (&acc)[2][2][4][2], const Unit& u, int wr, int wc, int fr, int fq, const PG8_LAS float*) const {
;     ...
;             for (int m = 0; m < 4; ++m) { const int row = row0 + ai * HALF + m * 16; const size_t off = (size_t)row * ldc + col0; float ss = 0.f;
; #pragma unroll
;                 for (int bj = 0; bj < 2; ++bj) {
;                     const f32x4 b0 = *(const f32x4*)(base + off + bj * HALF), b1 = *(const f32x4*)(base + off + bj * HALF + 4);
;                     const f32x4 v0 = b0 + acc[ai][bj][m][0], v1 = b1 + acc[ai][bj][m][1];
;                     *(f32x4*)(out + off + bj * HALF) = v0; *(f32x4*)(out + off + bj * HALF + 4) = v1;
;                     if (xb) { u32x4 w; w.x = cvt_pk_bf16(v0[0], v0[1]); w.y = cvt_pk_bf16(v0[2], v0[3]); w.z = cvt_pk_bf16(v1[0], v1[1]); w.w = cvt_pk_bf16(v1[2], v1[3]);
;                         *(u32x4*)(xb + off + bj * HALF) = w;
;                         ss += ((v0[0] * v0[0] + v0[1] * v0[1]) + (v0[2] * v0[2] + v0[3] * v0[3])) + ((v1[0] * v1[0] + v1[1] * v1[1]) + (v1[2] * v1[2] + v1[3] * v1[3])); } }
;                 if (xb) { ss += __shfl_xor(ss, 16); ss += __shfl_xor(ss, 32); if (fq == 0) ssq[(size_t)row * 16 + u.pn * 4 + wc] = ss; } }
.LBB0_851:
	s_or_b64 exec, exec, s[24:25]
	v_or_b32_e32 v80, 48, v146
	s_waitcnt lgkmcnt(0)
	v_ashrrev_i32_e32 v81, 31, v80
	v_lshlrev_b64 v[82:83], 10, v[80:81]
	v_lshl_add_u64 v[90:91], v[82:83], 0, v[144:145]
	v_lshl_add_u64 v[92:93], v[90:91], 2, s[68:69]
	global_load_dwordx4 v[216:219], v[174:175], off offset:512
	global_load_dwordx4 v[228:231], v[174:175], off offset:528
	v_lshl_add_u64 v[174:175], v[174:175], 0, s[98:99]
	v_readlane_b32 s24, v254, 39
	v_readlane_b32 s25, v254, 40
	s_waitcnt vmcnt(33)
	v_pk_add_f32 v[78:79], v[78:79], v[234:235]
	v_pk_add_f32 v[76:77], v[76:77], v[232:233]
	s_waitcnt vmcnt(32)
	v_pk_add_f32 v[74:75], v[74:75], v[238:239]
	v_pk_add_f32 v[72:73], v[72:73], v[236:237]
	v_lshl_add_u64 v[90:91], v[90:91], 1, s[24:25]
	v_cvt_pk_bf16_f32 v82, v76, v77
	v_cvt_pk_bf16_f32 v83, v78, v79
	v_cvt_pk_bf16_f32 v84, v72, v73
	v_cvt_pk_bf16_f32 v85, v74, v75
	global_store_dwordx4 v[92:93], v[76:79], off
	global_store_dwordx4 v[92:93], v[72:75], off offset:16
	global_store_dwordx4 v[90:91], v[82:85], off
	global_load_dwordx4 v[232:235], v[174:175], off
	global_load_dwordx4 v[236:239], v[174:175], off offset:16
	s_nop 0
	v_mul_f32_e32 v77, v77, v77
	v_mul_f32_e32 v79, v79, v79
	v_mul_f32_e32 v73, v73, v73
	v_mul_f32_e32 v75, v75, v75
	v_fmac_f32_e32 v77, v76, v76
	v_fmac_f32_e32 v79, v78, v78
	v_fmac_f32_e32 v73, v72, v72
	v_fmac_f32_e32 v75, v74, v74
	v_add_f32_e32 v72, v77, v79
	v_add_f32_e32 v73, v73, v75
	v_add_f32_e32 v76, v72, v73
	s_waitcnt vmcnt(36)
	v_pk_add_f32 v[70:71], v[70:71], v[242:243]
	v_pk_add_f32 v[68:69], v[68:69], v[240:241]
	s_waitcnt vmcnt(35)
	v_pk_add_f32 v[74:75], v[66:67], v[246:247]
	v_pk_add_f32 v[72:73], v[64:65], v[244:245]
	v_mul_f32_e32 v64, v69, v69
	v_mul_f32_e32 v65, v71, v71
	v_mul_f32_e32 v66, v73, v73
	v_mul_f32_e32 v67, v75, v75
	v_fmac_f32_e32 v64, v68, v68
	v_fmac_f32_e32 v65, v70, v70
	v_fmac_f32_e32 v66, v72, v72
	v_fmac_f32_e32 v67, v74, v74
	v_add_f32_e32 v64, v64, v65
	v_add_f32_e32 v65, v66, v67
	v_add_f32_e32 v64, v64, v65
	v_add_f32_e32 v64, v76, v64
	ds_bpermute_b32 v65, v120, v64
	global_store_dwordx4 v[92:93], v[68:71], off offset:512
	global_store_dwordx4 v[92:93], v[72:75], off offset:528
	v_cvt_pk_bf16_f32 v66, v68, v69
	v_cvt_pk_bf16_f32 v67, v70, v71
	v_cvt_pk_bf16_f32 v68, v72, v73
	s_waitcnt lgkmcnt(0)
	v_add_f32_e32 v64, v64, v65
	ds_bpermute_b32 v65, v114, v64
	v_cvt_pk_bf16_f32 v69, v74, v75
	global_store_dwordx4 v[90:91], v[66:69], off offset:256
	s_and_saveexec_b64 s[24:25], s[2:3]
	s_cbranch_execz .LBB0_853
	v_readlane_b32 s26, v254, 41
	s_waitcnt lgkmcnt(0)
	v_add_f32_e32 v66, v64, v65
	v_lshlrev_b64 v[64:65], 6, v[80:81]
	v_readlane_b32 s27, v254, 42
	s_lshl_b32 s6, s38, 2
	s_nop 0
	v_lshl_add_u64 v[64:65], s[26:27], 0, v[64:65]
	v_lshl_add_u64 v[64:65], s[22:23], 2, v[64:65]
	v_lshl_add_u64 v[64:65], v[64:65], 0, s[6:7]
	global_store_dword v[64:65], v66, off
.LBB0_853:
	s_or_b64 exec, exec, s[24:25]
	v_add_u32_e32 v64, 0x80, v146
	s_waitcnt lgkmcnt(0)
	v_ashrrev_i32_e32 v65, 31, v64
	v_lshlrev_b64 v[66:67], 10, v[64:65]
	v_lshl_add_u64 v[74:75], v[66:67], 0, v[144:145]
	v_lshl_add_u64 v[76:77], v[74:75], 2, s[68:69]
	global_load_dwordx4 v[240:243], v[174:175], off offset:512
	global_load_dwordx4 v[244:247], v[174:175], off offset:528
	v_readlane_b32 s24, v254, 39
	v_readlane_b32 s25, v254, 40
	s_waitcnt vmcnt(36)
	v_pk_add_f32 v[62:63], v[62:63], v[178:179]
	v_pk_add_f32 v[60:61], v[60:61], v[176:177]
	s_waitcnt vmcnt(35)
	v_pk_add_f32 v[58:59], v[58:59], v[182:183]
	v_pk_add_f32 v[56:57], v[56:57], v[180:181]
	v_lshl_add_u64 v[74:75], v[74:75], 1, s[24:25]
	v_cvt_pk_bf16_f32 v66, v60, v61
	v_cvt_pk_bf16_f32 v67, v62, v63
	v_cvt_pk_bf16_f32 v68, v56, v57
	v_cvt_pk_bf16_f32 v69, v58, v59
	global_store_dwordx4 v[76:77], v[60:63], off
	global_store_dwordx4 v[76:77], v[56:59], off offset:16
	global_store_dwordx4 v[74:75], v[66:69], off
	s_nop 0
	v_mul_f32_e32 v61, v61, v61
	v_mul_f32_e32 v63, v63, v63
	v_mul_f32_e32 v57, v57, v57
	v_mul_f32_e32 v59, v59, v59
	v_fmac_f32_e32 v61, v60, v60
	v_fmac_f32_e32 v63, v62, v62
	v_fmac_f32_e32 v57, v56, v56
	v_fmac_f32_e32 v59, v58, v58
	v_add_f32_e32 v56, v61, v63
	v_add_f32_e32 v57, v57, v59
	v_add_f32_e32 v60, v56, v57
	s_waitcnt vmcnt(34)
	v_pk_add_f32 v[54:55], v[54:55], v[186:187]
	v_pk_add_f32 v[52:53], v[52:53], v[184:185]
	s_waitcnt vmcnt(33)
	v_pk_add_f32 v[58:59], v[50:51], v[190:191]
	v_pk_add_f32 v[56:57], v[48:49], v[188:189]
	v_mul_f32_e32 v48, v53, v53
	v_mul_f32_e32 v49, v55, v55
	v_mul_f32_e32 v50, v57, v57
	v_mul_f32_e32 v51, v59, v59
	v_fmac_f32_e32 v48, v52, v52
	v_fmac_f32_e32 v49, v54, v54
	v_fmac_f32_e32 v50, v56, v56
	v_fmac_f32_e32 v51, v58, v58
	v_add_f32_e32 v48, v48, v49
	v_add_f32_e32 v49, v50, v51
	v_add_f32_e32 v48, v48, v49
	v_add_f32_e32 v48, v60, v48
	ds_bpermute_b32 v49, v120, v48
	global_store_dwordx4 v[76:77], v[52:55], off offset:512
	global_store_dwordx4 v[76:77], v[56:59], off offset:528
	v_cvt_pk_bf16_f32 v50, v52, v53
	v_cvt_pk_bf16_f32 v51, v54, v55
	v_cvt_pk_bf16_f32 v52, v56, v57
	s_waitcnt lgkmcnt(0)
	v_add_f32_e32 v48, v48, v49
	ds_bpermute_b32 v49, v114, v48
	v_cvt_pk_bf16_f32 v53, v58, v59
	global_store_dwordx4 v[74:75], v[50:53], off offset:256
	s_and_saveexec_b64 s[24:25], s[2:3]
	s_cbranch_execz .LBB0_855
	v_readlane_b32 s26, v254, 41
	s_waitcnt lgkmcnt(0)
	v_add_f32_e32 v50, v48, v49
	v_lshlrev_b64 v[48:49], 6, v[64:65]
	v_readlane_b32 s27, v254, 42
	s_lshl_b32 s6, s38, 2
	s_nop 0
	v_lshl_add_u64 v[48:49], s[26:27], 0, v[48:49]
	v_lshl_add_u64 v[48:49], s[22:23], 2, v[48:49]
	v_lshl_add_u64 v[48:49], v[48:49], 0, s[6:7]
	global_store_dword v[48:49], v50, off
; __device__ __forceinline__ unsigned cvt_pk_bf16(float lo, float hi) { const f32x2_t v = {lo, hi}; const bf16x2_t b = __builtin_convertvector(v, bf16x2_t); return __builtin_bit_cast(unsigned, b); }
;     __device__ __forceinline__ void operator()(const f32x4 (&acc)[2][2][4][2], const Unit& u, int wr, int wc, int fr, int fq, const PG8_LAS float*) const {
;     ...
;             for (int m = 0; m < 4; ++m) { const int row = row0 + ai * HALF + m * 16; const size_t off = (size_t)row * ldc + col0; float ss = 0.f;
; #pragma unroll
;                 for (int bj = 0; bj < 2; ++bj) {
;                     const f32x4 b0 = *(const f32x4*)(base + off + bj * HALF), b1 = *(const f32x4*)(base + off + bj * HALF + 4);
;                     const f32x4 v0 = b0 + acc[ai][bj][m][0], v1 = b1 + acc[ai][bj][m][1];
;                     *(f32x4*)(out + off + bj * HALF) = v0; *(f32x4*)(out + off + bj * HALF + 4) = v1;
;                     if (xb) { u32x4 w; w.x = cvt_pk_bf16(v0[0], v0[1]); w.y = cvt_pk_bf16(v0[2], v0[3]); w.z = cvt_pk_bf16(v1[0], v1[1]); w.w = cvt_pk_bf16(v1[2], v1[3]);
;                         *(u32x4*)(xb + off + bj * HALF) = w;
;                         ss += ((v0[0] * v0[0] + v0[1] * v0[1]) + (v0[2] * v0[2] + v0[3] * v0[3])) + ((v1[0] * v1[0] + v1[1] * v1[1]) + (v1[2] * v1[2] + v1[3] * v1[3])); } }
;                 if (xb) { ss += __shfl_xor(ss, 16); ss += __shfl_xor(ss, 32); if (fq == 0) ssq[(size_t)row * 16 + u.pn * 4 + wc] = ss; } }
.LBB0_855:
	s_or_b64 exec, exec, s[24:25]
	v_add_u32_e32 v48, 0x90, v146
	s_waitcnt lgkmcnt(0)
	v_ashrrev_i32_e32 v49, 31, v48
	v_lshlrev_b64 v[50:51], 10, v[48:49]
	v_lshl_add_u64 v[58:59], v[50:51], 0, v[144:145]
	v_lshl_add_u64 v[60:61], v[58:59], 2, s[68:69]
	v_readlane_b32 s24, v254, 39
	v_readlane_b32 s25, v254, 40
	s_waitcnt vmcnt(32)
	v_pk_add_f32 v[46:47], v[46:47], v[194:195]
	v_pk_add_f32 v[44:45], v[44:45], v[192:193]
	s_waitcnt vmcnt(31)
	v_pk_add_f32 v[42:43], v[42:43], v[198:199]
	v_pk_add_f32 v[40:41], v[40:41], v[196:197]
	v_lshl_add_u64 v[58:59], v[58:59], 1, s[24:25]
	v_cvt_pk_bf16_f32 v50, v44, v45
	v_cvt_pk_bf16_f32 v51, v46, v47
	v_cvt_pk_bf16_f32 v52, v40, v41
	v_cvt_pk_bf16_f32 v53, v42, v43
	global_store_dwordx4 v[60:61], v[44:47], off
	global_store_dwordx4 v[60:61], v[40:43], off offset:16
	global_store_dwordx4 v[58:59], v[50:53], off
	s_nop 0
	v_mul_f32_e32 v45, v45, v45
	v_mul_f32_e32 v47, v47, v47
	v_mul_f32_e32 v41, v41, v41
	v_mul_f32_e32 v43, v43, v43
	v_fmac_f32_e32 v45, v44, v44
	v_fmac_f32_e32 v47, v46, v46
	v_fmac_f32_e32 v41, v40, v40
	v_fmac_f32_e32 v43, v42, v42
	v_add_f32_e32 v40, v45, v47
	v_add_f32_e32 v41, v41, v43
	v_add_f32_e32 v44, v40, v41
	s_waitcnt vmcnt(30)
	v_pk_add_f32 v[38:39], v[38:39], v[202:203]
	v_pk_add_f32 v[36:37], v[36:37], v[200:201]
	s_waitcnt vmcnt(29)
	v_pk_add_f32 v[42:43], v[34:35], v[206:207]
	v_pk_add_f32 v[40:41], v[32:33], v[204:205]
	v_mul_f32_e32 v32, v37, v37
	v_mul_f32_e32 v33, v39, v39
	v_mul_f32_e32 v34, v41, v41
	v_mul_f32_e32 v35, v43, v43
	v_fmac_f32_e32 v32, v36, v36
	v_fmac_f32_e32 v33, v38, v38
	v_fmac_f32_e32 v34, v40, v40
	v_fmac_f32_e32 v35, v42, v42
	v_add_f32_e32 v32, v32, v33
	v_add_f32_e32 v33, v34, v35
	v_add_f32_e32 v32, v32, v33
	v_add_f32_e32 v32, v44, v32
	ds_bpermute_b32 v33, v120, v32
	global_store_dwordx4 v[60:61], v[36:39], off offset:512
	global_store_dwordx4 v[60:61], v[40:43], off offset:528
	v_cvt_pk_bf16_f32 v34, v36, v37
	v_cvt_pk_bf16_f32 v35, v38, v39
	v_cvt_pk_bf16_f32 v36, v40, v41
	s_waitcnt lgkmcnt(0)
	v_add_f32_e32 v32, v32, v33
	ds_bpermute_b32 v33, v114, v32
	v_cvt_pk_bf16_f32 v37, v42, v43
	global_store_dwordx4 v[58:59], v[34:37], off offset:256
	s_and_saveexec_b64 s[24:25], s[2:3]
	s_cbranch_execz .LBB0_857
	v_readlane_b32 s26, v254, 41
	s_waitcnt lgkmcnt(0)
	v_add_f32_e32 v34, v32, v33
	v_lshlrev_b64 v[32:33], 6, v[48:49]
	v_readlane_b32 s27, v254, 42
	s_lshl_b32 s6, s38, 2
	s_nop 0
	v_lshl_add_u64 v[32:33], s[26:27], 0, v[32:33]
	v_lshl_add_u64 v[32:33], s[22:23], 2, v[32:33]
	v_lshl_add_u64 v[32:33], v[32:33], 0, s[6:7]
	global_store_dword v[32:33], v34, off
; __device__ __forceinline__ unsigned cvt_pk_bf16(float lo, float hi) { const f32x2_t v = {lo, hi}; const bf16x2_t b = __builtin_convertvector(v, bf16x2_t); return __builtin_bit_cast(unsigned, b); }
;     __device__ __forceinline__ void operator()(const f32x4 (&acc)[2][2][4][2], const Unit& u, int wr, int wc, int fr, int fq, const PG8_LAS float*) const {
;     ...
;             for (int m = 0; m < 4; ++m) { const int row = row0 + ai * HALF + m * 16; const size_t off = (size_t)row * ldc + col0; float ss = 0.f;
; #pragma unroll
;                 for (int bj = 0; bj < 2; ++bj) {
;                     const f32x4 b0 = *(const f32x4*)(base + off + bj * HALF), b1 = *(const f32x4*)(base + off + bj * HALF + 4);
;                     const f32x4 v0 = b0 + acc[ai][bj][m][0], v1 = b1 + acc[ai][bj][m][1];
;                     *(f32x4*)(out + off + bj * HALF) = v0; *(f32x4*)(out + off + bj * HALF + 4) = v1;
;                     if (xb) { u32x4 w; w.x = cvt_pk_bf16(v0[0], v0[1]); w.y = cvt_pk_bf16(v0[2], v0[3]); w.z = cvt_pk_bf16(v1[0], v1[1]); w.w = cvt_pk_bf16(v1[2], v1[3]);
;                         *(u32x4*)(xb + off + bj * HALF) = w;
;                         ss += ((v0[0] * v0[0] + v0[1] * v0[1]) + (v0[2] * v0[2] + v0[3] * v0[3])) + ((v1[0] * v1[0] + v1[1] * v1[1]) + (v1[2] * v1[2] + v1[3] * v1[3])); } }
;                 if (xb) { ss += __shfl_xor(ss, 16); ss += __shfl_xor(ss, 32); if (fq == 0) ssq[(size_t)row * 16 + u.pn * 4 + wc] = ss; } }
.LBB0_857:
	s_or_b64 exec, exec, s[24:25]
	v_add_u32_e32 v32, 0xa0, v146
	s_waitcnt lgkmcnt(0)
	v_ashrrev_i32_e32 v33, 31, v32
	v_lshlrev_b64 v[34:35], 10, v[32:33]
	v_lshl_add_u64 v[42:43], v[34:35], 0, v[144:145]
	v_lshl_add_u64 v[44:45], v[42:43], 2, s[68:69]
	v_readlane_b32 s24, v254, 39
	v_readlane_b32 s25, v254, 40
	s_waitcnt vmcnt(28)
	v_pk_add_f32 v[30:31], v[30:31], v[210:211]
	v_pk_add_f32 v[28:29], v[28:29], v[208:209]
	s_waitcnt vmcnt(27)
	v_pk_add_f32 v[26:27], v[26:27], v[214:215]
	v_pk_add_f32 v[24:25], v[24:25], v[212:213]
	v_lshl_add_u64 v[42:43], v[42:43], 1, s[24:25]
	v_cvt_pk_bf16_f32 v34, v28, v29
	v_cvt_pk_bf16_f32 v35, v30, v31
	v_cvt_pk_bf16_f32 v36, v24, v25
	v_cvt_pk_bf16_f32 v37, v26, v27
	global_store_dwordx4 v[44:45], v[28:31], off
	global_store_dwordx4 v[44:45], v[24:27], off offset:16
	global_store_dwordx4 v[42:43], v[34:37], off
	s_nop 0
	v_mul_f32_e32 v29, v29, v29
	v_mul_f32_e32 v31, v31, v31
	v_mul_f32_e32 v25, v25, v25
	v_mul_f32_e32 v27, v27, v27
	v_fmac_f32_e32 v29, v28, v28
	v_fmac_f32_e32 v31, v30, v30
	v_fmac_f32_e32 v25, v24, v24
	v_fmac_f32_e32 v27, v26, v26
	v_add_f32_e32 v24, v29, v31
	v_add_f32_e32 v25, v25, v27
	v_add_f32_e32 v28, v24, v25
	s_waitcnt vmcnt(26)
	v_pk_add_f32 v[22:23], v[22:23], v[218:219]
	v_pk_add_f32 v[20:21], v[20:21], v[216:217]
	s_waitcnt vmcnt(25)
	v_pk_add_f32 v[26:27], v[18:19], v[230:231]
	v_pk_add_f32 v[24:25], v[16:17], v[228:229]
	v_mul_f32_e32 v16, v21, v21
	v_mul_f32_e32 v17, v23, v23
	v_mul_f32_e32 v18, v25, v25
	v_mul_f32_e32 v19, v27, v27
	v_fmac_f32_e32 v16, v20, v20
	v_fmac_f32_e32 v17, v22, v22
	v_fmac_f32_e32 v18, v24, v24
	v_fmac_f32_e32 v19, v26, v26
	v_add_f32_e32 v16, v16, v17
	v_add_f32_e32 v17, v18, v19
	v_add_f32_e32 v16, v16, v17
	v_add_f32_e32 v16, v28, v16
	ds_bpermute_b32 v17, v120, v16
	global_store_dwordx4 v[44:45], v[20:23], off offset:512
	global_store_dwordx4 v[44:45], v[24:27], off offset:528
	v_cvt_pk_bf16_f32 v18, v20, v21
	v_cvt_pk_bf16_f32 v19, v22, v23
	v_cvt_pk_bf16_f32 v20, v24, v25
	s_waitcnt lgkmcnt(0)
	v_add_f32_e32 v16, v16, v17
	ds_bpermute_b32 v17, v114, v16
	v_cvt_pk_bf16_f32 v21, v26, v27
	global_store_dwordx4 v[42:43], v[18:21], off offset:256
	s_and_saveexec_b64 s[24:25], s[2:3]
	s_cbranch_execz .LBB0_859
	v_readlane_b32 s26, v254, 41
	s_waitcnt lgkmcnt(0)
	v_add_f32_e32 v18, v16, v17
	v_lshlrev_b64 v[16:17], 6, v[32:33]
	v_readlane_b32 s27, v254, 42
	s_lshl_b32 s6, s38, 2
	s_nop 0
	v_lshl_add_u64 v[16:17], s[26:27], 0, v[16:17]
	v_lshl_add_u64 v[16:17], s[22:23], 2, v[16:17]
	v_lshl_add_u64 v[16:17], v[16:17], 0, s[6:7]
	global_store_dword v[16:17], v18, off
.LBB0_859:
	s_or_b64 exec, exec, s[24:25]
	v_add_u32_e32 v16, 0xb0, v146
	s_waitcnt lgkmcnt(0)
	v_ashrrev_i32_e32 v17, 31, v16
	v_lshlrev_b64 v[18:19], 10, v[16:17]
	v_lshl_add_u64 v[26:27], v[18:19], 0, v[144:145]
	v_lshl_add_u64 v[28:29], v[26:27], 2, s[68:69]
	v_readlane_b32 s24, v254, 39
	v_readlane_b32 s25, v254, 40
	s_waitcnt vmcnt(24)
	v_pk_add_f32 v[14:15], v[14:15], v[234:235]
	v_pk_add_f32 v[12:13], v[12:13], v[232:233]
	s_waitcnt vmcnt(23)
	v_pk_add_f32 v[10:11], v[10:11], v[238:239]
	v_pk_add_f32 v[8:9], v[8:9], v[236:237]
	v_lshl_add_u64 v[26:27], v[26:27], 1, s[24:25]
	v_cvt_pk_bf16_f32 v18, v12, v13
	v_cvt_pk_bf16_f32 v19, v14, v15
	v_cvt_pk_bf16_f32 v20, v8, v9
	v_cvt_pk_bf16_f32 v21, v10, v11
	global_store_dwordx4 v[28:29], v[12:15], off
	global_store_dwordx4 v[28:29], v[8:11], off offset:16
	global_store_dwordx4 v[26:27], v[18:21], off
	s_nop 0
	v_mul_f32_e32 v13, v13, v13
	v_mul_f32_e32 v15, v15, v15
	v_mul_f32_e32 v9, v9, v9
	v_mul_f32_e32 v11, v11, v11
	v_fmac_f32_e32 v13, v12, v12
	v_fmac_f32_e32 v15, v14, v14
	v_fmac_f32_e32 v9, v8, v8
	v_fmac_f32_e32 v11, v10, v10
	v_add_f32_e32 v8, v13, v15
	v_add_f32_e32 v9, v9, v11
	v_add_f32_e32 v12, v8, v9
	s_waitcnt vmcnt(22)
	v_pk_add_f32 v[6:7], v[6:7], v[242:243]
	v_pk_add_f32 v[4:5], v[4:5], v[240:241]
	s_waitcnt vmcnt(21)
	v_pk_add_f32 v[10:11], v[2:3], v[246:247]
	v_pk_add_f32 v[8:9], v[0:1], v[244:245]
	v_mul_f32_e32 v0, v5, v5
	v_mul_f32_e32 v1, v7, v7
	v_mul_f32_e32 v2, v9, v9
	v_mul_f32_e32 v3, v11, v11
	v_fmac_f32_e32 v0, v4, v4
	v_fmac_f32_e32 v1, v6, v6
	v_fmac_f32_e32 v2, v8, v8
	v_fmac_f32_e32 v3, v10, v10
	v_add_f32_e32 v0, v0, v1
	v_add_f32_e32 v1, v2, v3
	v_add_f32_e32 v0, v0, v1
	v_add_f32_e32 v0, v12, v0
	ds_bpermute_b32 v1, v120, v0
	global_store_dwordx4 v[28:29], v[4:7], off offset:512
	global_store_dwordx4 v[28:29], v[8:11], off offset:528
	v_cvt_pk_bf16_f32 v2, v4, v5
	v_cvt_pk_bf16_f32 v3, v6, v7
	v_cvt_pk_bf16_f32 v4, v8, v9
	s_waitcnt lgkmcnt(0)
	v_add_f32_e32 v0, v0, v1
	ds_bpermute_b32 v1, v114, v0
	v_cvt_pk_bf16_f32 v5, v10, v11
	global_store_dwordx4 v[26:27], v[2:5], off offset:256
	s_and_saveexec_b64 s[24:25], s[2:3]
	s_cbranch_execz .LBB0_861
	v_readlane_b32 s26, v254, 41
	s_waitcnt lgkmcnt(0)
	v_add_f32_e32 v2, v0, v1
	v_lshlrev_b64 v[0:1], 6, v[16:17]
	v_readlane_b32 s27, v254, 42
	s_lshl_b32 s6, s38, 2
	s_nop 0
	v_lshl_add_u64 v[0:1], s[26:27], 0, v[0:1]
	v_lshl_add_u64 v[0:1], s[22:23], 2, v[0:1]
	v_lshl_add_u64 v[0:1], v[0:1], 0, s[6:7]
	global_store_dword v[0:1], v2, off

; #define PG8_LAS __attribute__((address_space(3)))
;     __device__ __forceinline__ void operator()(const f32x4 (&acc)[2][2][4][2], const Unit& u, int wr, int wc, int fr, int fq, const PG8_LAS float*) const {
;         const int row0 = u.pm * BM + wr * 64 + fr; const int col0 = u.pn * BM + wc * 32 + 8 * fq;
; #pragma unroll
;         for (int ai = 0; ai < 2; ++ai)
; #pragma unroll
;             for (int m = 0; m < 4; ++m) { const int row = row0 + ai * HALF + m * 16; const size_t off = (size_t)row * ldc + col0; float ss = 0.f;
; #pragma unroll
;                 for (int bj = 0; bj < 2; ++bj) {
;                     const f32x4 b0 = *(const f32x4*)(base + off + bj * HALF), b1 = *(const f32x4*)(base + off + bj * HALF + 4);
;                     const f32x4 v0 = b0 + acc[ai][bj][m][0], v1 = b1 + acc[ai][bj][m][1];
;                     *(f32x4*)(out + off + bj * HALF) = v0; *(f32x4*)(out + off + bj * HALF + 4) = v1;
.LBB0_1644:
	v_lshl_add_u32 v146, s26, 8, v150
	v_lshl_or_b32 v144, s27, 8, v152
	v_ashrrev_i32_e32 v147, 31, v146
	v_ashrrev_i32_e32 v145, 31, v144
	v_lshlrev_b64 v[148:149], 12, v[146:147]
	v_lshl_add_u64 v[156:157], s[68:69], 0, v[148:149]
	v_lshlrev_b64 v[148:149], 2, v[144:145]
	v_lshl_add_u64 v[144:145], v[156:157], 0, v[148:149]
	v_mov_b32_e32 v236, v144
	v_mov_b32_e32 v237, v145
	s_mov_b64 s[98:99], 0x10000
	s_mov_b64 s[100:101], 0x50000
	global_load_dwordx4 v[164:167], v[236:237], off offset:16
	global_load_dwordx4 v[168:171], v[236:237], off
	global_load_dwordx4 v[172:175], v[236:237], off offset:528
	global_load_dwordx4 v[176:179], v[236:237], off offset:512
	v_lshl_add_u64 v[236:237], v[236:237], 0, s[98:99]
	global_load_dwordx4 v[180:183], v[236:237], off offset:16
	global_load_dwordx4 v[184:187], v[236:237], off
	global_load_dwordx4 v[188:191], v[236:237], off offset:528
	global_load_dwordx4 v[192:195], v[236:237], off offset:512
	v_lshl_add_u64 v[236:237], v[236:237], 0, s[98:99]
	global_load_dwordx4 v[196:199], v[236:237], off offset:16
	global_load_dwordx4 v[200:203], v[236:237], off
	global_load_dwordx4 v[204:207], v[236:237], off offset:528
	global_load_dwordx4 v[208:211], v[236:237], off offset:512
	v_lshl_add_u64 v[236:237], v[236:237], 0, s[98:99]
	global_load_dwordx4 v[212:215], v[236:237], off offset:16
	global_load_dwordx4 v[224:227], v[236:237], off
	global_load_dwordx4 v[228:231], v[236:237], off offset:528
	global_load_dwordx4 v[232:235], v[236:237], off offset:512
	v_lshl_add_u64 v[236:237], v[236:237], 0, s[100:101]
	s_mov_b64 s[26:27], -1
	s_waitcnt vmcnt(14)
	v_pk_add_f32 v[122:123], v[122:123], v[166:167]
	v_pk_add_f32 v[126:127], v[126:127], v[170:171]
	v_pk_add_f32 v[124:125], v[124:125], v[168:169]
	v_pk_add_f32 v[120:121], v[120:121], v[164:165]
	global_store_dwordx4 v[144:145], v[124:127], off
	global_store_dwordx4 v[144:145], v[120:123], off offset:16
	global_load_dwordx4 v[164:167], v[236:237], off
	global_load_dwordx4 v[168:171], v[236:237], off offset:16
	s_nop 0
	s_waitcnt vmcnt(17)
	v_pk_add_f32 v[112:113], v[112:113], v[172:173]
	s_waitcnt vmcnt(16)
	v_pk_add_f32 v[118:119], v[118:119], v[178:179]
	v_pk_add_f32 v[116:117], v[116:117], v[176:177]
	v_pk_add_f32 v[114:115], v[114:115], v[174:175]
	global_store_dwordx4 v[144:145], v[116:119], off offset:512
	global_store_dwordx4 v[144:145], v[112:115], off offset:528
	s_nop 1
	v_or_b32_e32 v112, 16, v146
	v_ashrrev_i32_e32 v113, 31, v112
	v_lshlrev_b64 v[112:113], 12, v[112:113]
	v_lshl_add_u64 v[112:113], s[68:69], 0, v[112:113]
	v_lshl_add_u64 v[120:121], v[112:113], 0, v[148:149]
	global_load_dwordx4 v[172:175], v[236:237], off offset:528
	global_load_dwordx4 v[176:179], v[236:237], off offset:512
	v_lshl_add_u64 v[236:237], v[236:237], 0, s[98:99]
	s_waitcnt vmcnt(19)
	v_pk_add_f32 v[106:107], v[106:107], v[182:183]
	s_waitcnt vmcnt(18)
	v_pk_add_f32 v[110:111], v[110:111], v[186:187]
	v_pk_add_f32 v[108:109], v[108:109], v[184:185]
	v_pk_add_f32 v[104:105], v[104:105], v[180:181]
	global_store_dwordx4 v[120:121], v[108:111], off
	global_store_dwordx4 v[120:121], v[104:107], off offset:16
	global_load_dwordx4 v[180:183], v[236:237], off
	global_load_dwordx4 v[184:187], v[236:237], off offset:16
	s_nop 0
	s_waitcnt vmcnt(21)
	v_pk_add_f32 v[96:97], v[96:97], v[188:189]
	s_waitcnt vmcnt(20)
	v_pk_add_f32 v[102:103], v[102:103], v[194:195]
	v_pk_add_f32 v[100:101], v[100:101], v[192:193]
	v_pk_add_f32 v[98:99], v[98:99], v[190:191]
	global_store_dwordx4 v[120:121], v[100:103], off offset:512
	global_store_dwordx4 v[120:121], v[96:99], off offset:528
	s_nop 1
	v_or_b32_e32 v96, 32, v146
	v_ashrrev_i32_e32 v97, 31, v96
	v_lshlrev_b64 v[96:97], 12, v[96:97]
	v_lshl_add_u64 v[96:97], s[68:69], 0, v[96:97]
	v_lshl_add_u64 v[104:105], v[96:97], 0, v[148:149]
	global_load_dwordx4 v[188:191], v[236:237], off offset:528
	global_load_dwordx4 v[192:195], v[236:237], off offset:512
	v_lshl_add_u64 v[236:237], v[236:237], 0, s[98:99]
	s_waitcnt vmcnt(23)
	v_pk_add_f32 v[90:91], v[90:91], v[198:199]
	s_waitcnt vmcnt(22)
	v_pk_add_f32 v[94:95], v[94:95], v[202:203]
	v_pk_add_f32 v[92:93], v[92:93], v[200:201]
	v_pk_add_f32 v[88:89], v[88:89], v[196:197]
	global_store_dwordx4 v[104:105], v[92:95], off
	global_store_dwordx4 v[104:105], v[88:91], off offset:16
	global_load_dwordx4 v[196:199], v[236:237], off
	global_load_dwordx4 v[200:203], v[236:237], off offset:16
	s_nop 0
	s_waitcnt vmcnt(25)
	v_pk_add_f32 v[80:81], v[80:81], v[204:205]
	s_waitcnt vmcnt(24)
; #define PG8_LAS __attribute__((address_space(3)))
;     __device__ __forceinline__ void operator()(const f32x4 (&acc)[2][2][4][2], const Unit& u, int wr, int wc, int fr, int fq, const PG8_LAS float*) const {
;         const int row0 = u.pm * BM + wr * 64 + fr; const int col0 = u.pn * BM + wc * 32 + 8 * fq;
; #pragma unroll
;         for (int ai = 0; ai < 2; ++ai)
; #pragma unroll
;             for (int m = 0; m < 4; ++m) { const int row = row0 + ai * HALF + m * 16; const size_t off = (size_t)row * ldc + col0; float ss = 0.f;
; #pragma unroll
;                 for (int bj = 0; bj < 2; ++bj) {
;                     const f32x4 b0 = *(const f32x4*)(base + off + bj * HALF), b1 = *(const f32x4*)(base + off + bj * HALF + 4);
;                     const f32x4 v0 = b0 + acc[ai][bj][m][0], v1 = b1 + acc[ai][bj][m][1];
;                     *(f32x4*)(out + off + bj * HALF) = v0; *(f32x4*)(out + off + bj * HALF + 4) = v1;
	v_pk_add_f32 v[86:87], v[86:87], v[210:211]
	v_pk_add_f32 v[84:85], v[84:85], v[208:209]
	v_pk_add_f32 v[82:83], v[82:83], v[206:207]
	global_store_dwordx4 v[104:105], v[84:87], off offset:512
	global_store_dwordx4 v[104:105], v[80:83], off offset:528
	s_nop 1
	v_or_b32_e32 v80, 48, v146
	v_ashrrev_i32_e32 v81, 31, v80
	v_lshlrev_b64 v[80:81], 12, v[80:81]
	v_lshl_add_u64 v[80:81], s[68:69], 0, v[80:81]
	v_lshl_add_u64 v[88:89], v[80:81], 0, v[148:149]
	global_load_dwordx4 v[204:207], v[236:237], off offset:528
	global_load_dwordx4 v[208:211], v[236:237], off offset:512
	v_lshl_add_u64 v[236:237], v[236:237], 0, s[98:99]
	s_waitcnt vmcnt(27)
	v_pk_add_f32 v[74:75], v[74:75], v[214:215]
	s_waitcnt vmcnt(26)
	v_pk_add_f32 v[78:79], v[78:79], v[226:227]
	v_pk_add_f32 v[76:77], v[76:77], v[224:225]
	v_pk_add_f32 v[72:73], v[72:73], v[212:213]
	global_store_dwordx4 v[88:89], v[76:79], off
	global_store_dwordx4 v[88:89], v[72:75], off offset:16
	global_load_dwordx4 v[212:215], v[236:237], off
	global_load_dwordx4 v[224:227], v[236:237], off offset:16
	s_nop 0
	s_waitcnt vmcnt(29)
	v_pk_add_f32 v[66:67], v[66:67], v[230:231]
	s_waitcnt vmcnt(28)
	v_pk_add_f32 v[70:71], v[70:71], v[234:235]
	v_pk_add_f32 v[68:69], v[68:69], v[232:233]
	v_add_co_u32_e32 v74, vcc, s50, v144
	v_pk_add_f32 v[64:65], v[64:65], v[228:229]
	global_store_dwordx4 v[88:89], v[68:71], off offset:512
	global_store_dwordx4 v[88:89], v[64:67], off offset:528
	v_addc_co_u32_e32 v75, vcc, 0, v145, vcc
	v_lshl_add_u64 v[72:73], v[144:145], 0, s[10:11]
	global_load_dwordx4 v[228:231], v[236:237], off offset:528
	global_load_dwordx4 v[232:235], v[236:237], off offset:512
	s_waitcnt vmcnt(29)
	v_pk_add_f32 v[62:63], v[62:63], v[166:167]
	v_pk_add_f32 v[60:61], v[60:61], v[164:165]
	s_waitcnt vmcnt(28)
	v_pk_add_f32 v[58:59], v[58:59], v[170:171]
	v_pk_add_f32 v[56:57], v[56:57], v[168:169]
	global_store_dwordx4 v[74:75], v[60:63], off
	global_store_dwordx4 v[72:73], v[56:59], off offset:16
	s_nop 0
	s_waitcnt vmcnt(27)
	v_pk_add_f32 v[50:51], v[50:51], v[174:175]
	s_waitcnt vmcnt(26)
	v_pk_add_f32 v[54:55], v[54:55], v[178:179]
	v_pk_add_f32 v[52:53], v[52:53], v[176:177]
	v_add_co_u32_e32 v58, vcc, s51, v144
	v_pk_add_f32 v[48:49], v[48:49], v[172:173]
	global_store_dwordx4 v[72:73], v[52:55], off offset:512
	global_store_dwordx4 v[72:73], v[48:51], off offset:528
	v_addc_co_u32_e32 v59, vcc, 0, v145, vcc
	v_lshl_add_u64 v[56:57], v[144:145], 0, s[12:13]
	s_waitcnt vmcnt(25)
	v_pk_add_f32 v[46:47], v[46:47], v[182:183]
	v_pk_add_f32 v[44:45], v[44:45], v[180:181]
	s_waitcnt vmcnt(24)
	v_pk_add_f32 v[42:43], v[42:43], v[186:187]
	v_pk_add_f32 v[40:41], v[40:41], v[184:185]
	global_store_dwordx4 v[58:59], v[44:47], off
	global_store_dwordx4 v[56:57], v[40:43], off offset:16
	s_nop 0
	s_waitcnt vmcnt(23)
	v_pk_add_f32 v[34:35], v[34:35], v[190:191]
	s_waitcnt vmcnt(22)
	v_pk_add_f32 v[38:39], v[38:39], v[194:195]
	v_pk_add_f32 v[36:37], v[36:37], v[192:193]
	v_add_co_u32_e32 v42, vcc, s52, v144
	v_pk_add_f32 v[32:33], v[32:33], v[188:189]
	global_store_dwordx4 v[56:57], v[36:39], off offset:512
	global_store_dwordx4 v[56:57], v[32:35], off offset:528
	v_addc_co_u32_e32 v43, vcc, 0, v145, vcc
	v_lshl_add_u64 v[40:41], v[144:145], 0, s[14:15]
	s_waitcnt vmcnt(21)
	v_pk_add_f32 v[30:31], v[30:31], v[198:199]
	v_pk_add_f32 v[28:29], v[28:29], v[196:197]
	s_waitcnt vmcnt(20)
	v_pk_add_f32 v[26:27], v[26:27], v[202:203]
	v_pk_add_f32 v[24:25], v[24:25], v[200:201]
	global_store_dwordx4 v[42:43], v[28:31], off
	global_store_dwordx4 v[40:41], v[24:27], off offset:16
	s_nop 0
	s_waitcnt vmcnt(19)
	v_pk_add_f32 v[18:19], v[18:19], v[206:207]
	s_waitcnt vmcnt(18)
	v_pk_add_f32 v[22:23], v[22:23], v[210:211]
	v_pk_add_f32 v[20:21], v[20:21], v[208:209]
	v_add_co_u32_e32 v26, vcc, s53, v144
	v_pk_add_f32 v[16:17], v[16:17], v[204:205]
	global_store_dwordx4 v[40:41], v[20:23], off offset:512
	global_store_dwordx4 v[40:41], v[16:19], off offset:528
	v_addc_co_u32_e32 v27, vcc, 0, v145, vcc
	s_nop 0
	v_lshl_add_u64 v[16:17], v[144:145], 0, s[16:17]
	s_andn2_b64 vcc, exec, s[2:3]
	s_waitcnt vmcnt(17)
	v_pk_add_f32 v[14:15], v[14:15], v[214:215]
	v_pk_add_f32 v[12:13], v[12:13], v[212:213]
	s_waitcnt vmcnt(16)
	v_pk_add_f32 v[10:11], v[10:11], v[226:227]
	v_pk_add_f32 v[8:9], v[8:9], v[224:225]
	global_store_dwordx4 v[26:27], v[12:15], off
	global_store_dwordx4 v[16:17], v[8:11], off offset:16
	s_nop 0
	s_waitcnt vmcnt(15)
	v_pk_add_f32 v[2:3], v[2:3], v[230:231]
	s_waitcnt vmcnt(14)
	v_pk_add_f32 v[6:7], v[6:7], v[234:235]
	v_pk_add_f32 v[4:5], v[4:5], v[232:233]
	v_pk_add_f32 v[0:1], v[0:1], v[228:229]
	global_store_dwordx4 v[16:17], v[4:7], off offset:512
	global_store_dwordx4 v[16:17], v[0:3], off offset:528
	s_cbranch_vccnz .LBB0_1633
	s_andn2_b64 vcc, exec, s[4:5]
	s_cbranch_vccnz .LBB0_1632
	s_barrier
	s_branch .LBB0_1632

; __global__ void __launch_bounds__(NTHREADS, 2) fwd_kernel(KArgs a) {
;     extern __shared__ __attribute__((aligned(16))) unsigned char lds_raw[];
	.amdhsa_kernel _Z10fwd_kernel5KArgs
		.amdhsa_group_segment_fixed_size 0
		.amdhsa_private_segment_fixed_size 0
		.amdhsa_kernarg_size 408
		.amdhsa_user_sgpr_count 2
		.amdhsa_user_sgpr_dispatch_ptr 0
		.amdhsa_user_sgpr_queue_ptr 0
		.amdhsa_user_sgpr_kernarg_segment_ptr 1
		.amdhsa_user_sgpr_dispatch_id 0
		.amdhsa_user_sgpr_kernarg_preload_length 0
		.amdhsa_user_sgpr_kernarg_preload_offset 0
		.amdhsa_user_sgpr_private_segment_size 0
		.amdhsa_uses_dynamic_stack 0
		.amdhsa_enable_private_segment 0
		.amdhsa_system_sgpr_workgroup_id_x 1
		.amdhsa_system_sgpr_workgroup_id_y 0
		.amdhsa_system_sgpr_workgroup_id_z 0
		.amdhsa_system_sgpr_workgroup_info 0
		.amdhsa_system_vgpr_workitem_id 2
		.amdhsa_next_free_vgpr 255
		.amdhsa_next_free_sgpr 102
		.amdhsa_accum_offset 256
		.amdhsa_reserve_vcc 1
		.amdhsa_float_round_mode_32 0
		.amdhsa_float_round_mode_16_64 0
		.amdhsa_float_denorm_mode_32 3
		.amdhsa_float_denorm_mode_16_64 3
		.amdhsa_dx10_clamp 1
		.amdhsa_ieee_mode 1
		.amdhsa_fp16_overflow 0
		.amdhsa_tg_split 0
		.amdhsa_exception_fp_ieee_invalid_op 0
		.amdhsa_exception_fp_denorm_src 0
		.amdhsa_exception_fp_ieee_div_zero 0
		.amdhsa_exception_fp_ieee_overflow 0
		.amdhsa_exception_fp_ieee_underflow 0
		.amdhsa_exception_fp_ieee_inexact 0
		.amdhsa_exception_int_div_zero 0
	.end_amdhsa_kernel

; __global__ void __launch_bounds__(NTHREADS, 2) fwd_kernel(KArgs a) {
;     extern __shared__ __attribute__((aligned(16))) unsigned char lds_raw[];
amdhsa.kernels:
  - .agpr_count:     0
    .args:
      - .offset:         0
        .size:           152
        .value_kind:     by_value
      - .offset:         152
        .size:           4
        .value_kind:     hidden_block_count_x
      - .offset:         156
        .size:           4
        .value_kind:     hidden_block_count_y
      - .offset:         160
        .size:           4
        .value_kind:     hidden_block_count_z
      - .offset:         164
        .size:           2
        .value_kind:     hidden_group_size_x
      - .offset:         166
        .size:           2
        .value_kind:     hidden_group_size_y
      - .offset:         168
        .size:           2
        .value_kind:     hidden_group_size_z
      - .offset:         170
        .size:           2
        .value_kind:     hidden_remainder_x
      - .offset:         172
        .size:           2
        .value_kind:     hidden_remainder_y
      - .offset:         174
        .size:           2
        .value_kind:     hidden_remainder_z
      - .offset:         192
        .size:           8
        .value_kind:     hidden_global_offset_x
      - .offset:         200
        .size:           8
        .value_kind:     hidden_global_offset_y
      - .offset:         208
        .size:           8
        .value_kind:     hidden_global_offset_z
      - .offset:         216
        .size:           2
        .value_kind:     hidden_grid_dims
      - .offset:         240
        .size:           8
        .value_kind:     hidden_multigrid_sync_arg
      - .offset:         272
        .size:           4
        .value_kind:     hidden_dynamic_lds_size
    .group_segment_fixed_size: 0
    .kernarg_segment_align: 8
    .kernarg_segment_size: 408
    .language:       OpenCL C
    .language_version:
      - 2
      - 0
    .max_flat_workgroup_size: 512
    .name:           _Z10fwd_kernel5KArgs
    .private_segment_fixed_size: 0
    .sgpr_count:     108
    .sgpr_spill_count: 151
    .symbol:         _Z10fwd_kernel5KArgs.kd
    .uniform_work_group_size: 1
    .uses_dynamic_stack: false
    .vgpr_count:     255
    .vgpr_spill_count: 0
    .wavefront_size: 64
